# attention PV sections: counted lgkmcnt waits per MFMA instead of a full LDS drain at each 4-MFMA group
# speedup vs baseline: 1.0045x; 1.0045x over previous
; __device__ __forceinline__ void partialSM(f32x16& p0, f32x16& p1, float& m_reg, float& mn, float& alpha, float C, float thrRaw) {
;   float pmax = p0[0];
; #pragma unroll
;   for (int r = 1; r < 16; ++r) pmax = fmaxf(pmax, p0[r]);
; #pragma unroll
;   for (int r = 0; r < 16; ++r) pmax = fmaxf(pmax, p1[r]);
;   { auto rr = __builtin_amdgcn_permlane32_swap(__float_as_uint(pmax), __float_as_uint(pmax), false, false);
;     pmax = fmaxf(__uint_as_float(rr[0]), __uint_as_float(rr[1])); }
;   if (__builtin_expect(__all(pmax - m_reg <= thrRaw), 1)) { mn = m_reg; alpha = 1.f; }
;   else { mn = fmaxf(m_reg, pmax); alpha = __builtin_amdgcn_exp2f((m_reg - mn) * C); m_reg = mn; }
;   float mnC = -mn * C;
; #pragma unroll
;   for (int r = 0; r < 16; ++r) p0[r] = fmaf(p0[r], C, mnC);
; #pragma unroll
;   for (int r = 0; r < 16; ++r) p1[r] = fmaf(p1[r], C, mnC);
; #pragma unroll
;   for (int r = 0; r < 16; ++r) p0[r] = __builtin_amdgcn_exp2f(p0[r]);
; }
; __device__ __forceinline__ void finishSM(f32x16& p0, f32x16& p1, float alpha, float& l_reg, bf16x8& pa0, bf16x8& pa1, bf16x8& pa2, bf16x8& pa3) {
; #pragma unroll
;   for (int r = 0; r < 16; ++r) p1[r] = __builtin_amdgcn_exp2f(p1[r]);
;   float ps = 0;
; #pragma unroll
;   for (int r = 0; r < 16; ++r) ps += p0[r];
; #pragma unroll
;   for (int r = 0; r < 16; ++r) ps += p1[r];
;   { auto rr = __builtin_amdgcn_permlane32_swap(__float_as_uint(ps), __float_as_uint(ps), false, false);
;     ps = __uint_as_float(rr[0]) + __uint_as_float(rr[1]); }
;   l_reg = l_reg * alpha + ps;
;     ...
;   PK4(p0, 0, pa0); PK4(p0, 8, pa1); PK4(p1, 0, pa2); PK4(p1, 8, pa3);
;     ...
; }
; template <int D0> __device__ __forceinline__ void pv_one(f32x16& od, int vb, bf16x8 pa0, bf16x8 pa1, bf16x8 pa2, bf16x8 pa3) {
;   const s16x4 l0 = tr_read<v_rd_off(D0, 0, 0)>(vb), h0 = tr_read<v_rd_off(D0, 0, 1)>(vb), l1 = tr_read<v_rd_off(D0, 1, 0)>(vb), h1 = tr_read<v_rd_off(D0, 1, 1)>(vb);
;   const s16x4 l2 = tr_read<v_rd_off(D0, 2, 0)>(vb), h2 = tr_read<v_rd_off(D0, 2, 1)>(vb), l3 = tr_read<v_rd_off(D0, 3, 0)>(vb), h3 = tr_read<v_rd_off(D0, 3, 1)>(vb);
;   asm volatile("s_waitcnt lgkmcnt(0)" ::: "memory"); SBAR();
;     ...
;   od = __builtin_amdgcn_mfma_f32_32x32x16_bf16(pa0, PK(l0, h0), od, 0, 0, 0);
;   od = __builtin_amdgcn_mfma_f32_32x32x16_bf16(pa1, PK(l1, h1), od, 0, 0, 0);
;   od = __builtin_amdgcn_mfma_f32_32x32x16_bf16(pa2, PK(l2, h2), od, 0, 0, 0);
.LBB0_513:
	s_or_b64 exec, exec, s[36:37]
	v_add_f32_e32 v2, 0, v94
	v_add_f32_e32 v2, v95, v2
	v_add_f32_e32 v2, v92, v2
	v_add_f32_e32 v2, v93, v2
	v_add_f32_e32 v2, v88, v2
	v_add_f32_e32 v2, v89, v2
	v_add_f32_e32 v2, v90, v2
	v_add_f32_e32 v2, v91, v2
	v_add_f32_e32 v2, v80, v2
	v_add_f32_e32 v2, v81, v2
	v_add_f32_e32 v2, v82, v2
	v_add_f32_e32 v2, v83, v2
	v_exp_f32_e32 v111, v144
	v_add_f32_e32 v2, v84, v2
	v_exp_f32_e32 v114, v145
	v_add_f32_e32 v2, v85, v2
	v_exp_f32_e32 v116, v142
	v_add_f32_e32 v2, v86, v2
	v_exp_f32_e32 v127, v143
	v_add_f32_e32 v2, v87, v2
	v_exp_f32_e32 v140, v140
	v_add_f32_e32 v2, v111, v2
	v_exp_f32_e32 v141, v141
	v_add_f32_e32 v2, v114, v2
	v_exp_f32_e32 v138, v138
	v_add_f32_e32 v2, v116, v2
	v_exp_f32_e32 v139, v139
	v_add_f32_e32 v2, v127, v2
	v_exp_f32_e32 v6, v136
	v_add_f32_e32 v2, v140, v2
	v_exp_f32_e32 v7, v137
	v_add_f32_e32 v2, v141, v2
	v_exp_f32_e32 v8, v134
	v_add_f32_e32 v2, v138, v2
	v_exp_f32_e32 v9, v135
	v_add_f32_e32 v2, v139, v2
	v_exp_f32_e32 v10, v132
	v_add_f32_e32 v2, v6, v2
	v_exp_f32_e32 v11, v133
	v_add_f32_e32 v2, v7, v2
	v_exp_f32_e32 v12, v130
	v_add_f32_e32 v2, v8, v2
	v_exp_f32_e32 v13, v131
	v_add_f32_e32 v2, v9, v2
	v_add_f32_e32 v2, v10, v2
	v_add_f32_e32 v2, v11, v2
	v_add_f32_e32 v2, v12, v2
	v_add_f32_e32 v112, v13, v2
	v_mov_b32_e32 v113, v112
	v_cvt_pk_bf16_f32 v2, v94, v95
	v_cvt_pk_bf16_f32 v3, v92, v93
	v_cvt_pk_bf16_f32 v4, v88, v89
	s_nop 1
	v_permlane32_swap_b32_e32 v112, v113
	v_cvt_pk_bf16_f32 v5, v90, v91
	v_permlane32_swap_b32_e32 v2, v4
	v_cvt_pk_bf16_f32 v88, v80, v81
	v_cvt_pk_bf16_f32 v89, v82, v83
	v_cvt_pk_bf16_f32 v90, v84, v85
	v_cvt_pk_bf16_f32 v91, v86, v87
	v_cvt_pk_bf16_f32 v92, v111, v114
	v_cvt_pk_bf16_f32 v93, v116, v127
	v_cvt_pk_bf16_f32 v94, v140, v141
	v_cvt_pk_bf16_f32 v95, v138, v139
	v_cvt_pk_bf16_f32 v130, v6, v7
	v_cvt_pk_bf16_f32 v131, v8, v9
	v_cvt_pk_bf16_f32 v132, v10, v11
	v_cvt_pk_bf16_f32 v133, v12, v13
	v_permlane32_swap_b32_e32 v3, v5
	v_permlane32_swap_b32_e32 v88, v90
	v_permlane32_swap_b32_e32 v89, v91
	v_permlane32_swap_b32_e32 v92, v94
	v_permlane32_swap_b32_e32 v93, v95
	v_permlane32_swap_b32_e32 v130, v132
	v_permlane32_swap_b32_e32 v131, v133
	s_mov_b32 s36, 0x50000
	v_add_co_u32_e32 v80, vcc, s36, v128
	s_nop 1
	v_addc_co_u32_e32 v81, vcc, 0, v129, vcc
	global_load_dwordx4 v[6:9], v[128:129], off offset:1024
	global_load_dwordx4 v[10:13], v[128:129], off
	global_load_dwordx4 v[84:87], v[80:81], off offset:1024
	s_nop 0
	global_load_dwordx4 v[80:83], v[80:81], off
	ds_read_b64_tr_b16 v[134:135], v151 offset:0
	ds_read_b64_tr_b16 v[136:137], v151 offset:0x800
	ds_read_b64_tr_b16 v[138:139], v151 offset:0x1000
	ds_read_b64_tr_b16 v[140:141], v151 offset:0x1800
	ds_read_b64_tr_b16 v[142:143], v151 offset:0x2000
	ds_read_b64_tr_b16 v[144:145], v151 offset:0x2800
	ds_read_b64_tr_b16 v[246:247], v151 offset:0x3000
	ds_read_b64_tr_b16 v[248:249], v151 offset:0x3800
	s_waitcnt lgkmcnt(6)
	s_nop 0
	v_mfma_f32_32x32x16_bf16 v[32:47], v[2:5], v[134:137], v[32:47]
	ds_read_b64_tr_b16 v[134:135], v151 offset:0x200
	ds_read_b64_tr_b16 v[136:137], v151 offset:0xa00
	s_waitcnt lgkmcnt(6)
	v_mfma_f32_32x32x16_bf16 v[32:47], v[88:91], v[138:141], v[32:47]
	ds_read_b64_tr_b16 v[138:139], v151 offset:0x1200
	ds_read_b64_tr_b16 v[140:141], v151 offset:0x1a00
	s_waitcnt lgkmcnt(6)
	v_mfma_f32_32x32x16_bf16 v[32:47], v[92:95], v[142:145], v[32:47]
	ds_read_b64_tr_b16 v[142:143], v151 offset:0x2200
	ds_read_b64_tr_b16 v[144:145], v151 offset:0x2a00
	s_waitcnt lgkmcnt(6)
	v_mfma_f32_32x32x16_bf16 v[32:47], v[130:133], v[246:249], v[32:47]
	ds_read_b64_tr_b16 v[246:247], v151 offset:0x3200
	ds_read_b64_tr_b16 v[248:249], v151 offset:0x3a00
	s_waitcnt lgkmcnt(6)
	v_mfma_f32_32x32x16_bf16 v[64:79], v[2:5], v[134:137], v[64:79]
	ds_read_b64_tr_b16 v[134:135], v151 offset:0x400
	ds_read_b64_tr_b16 v[136:137], v151 offset:0xc00
	s_waitcnt lgkmcnt(6)
	v_mfma_f32_32x32x16_bf16 v[64:79], v[88:91], v[138:141], v[64:79]
	ds_read_b64_tr_b16 v[138:139], v151 offset:0x1400
	ds_read_b64_tr_b16 v[140:141], v151 offset:0x1c00
	s_waitcnt lgkmcnt(6)
	v_mfma_f32_32x32x16_bf16 v[64:79], v[92:95], v[142:145], v[64:79]
	ds_read_b64_tr_b16 v[142:143], v151 offset:0x2400
	ds_read_b64_tr_b16 v[144:145], v151 offset:0x2c00
	s_waitcnt lgkmcnt(6)
	v_mfma_f32_32x32x16_bf16 v[64:79], v[130:133], v[246:249], v[64:79]
	ds_read_b64_tr_b16 v[246:247], v151 offset:0x3400
	ds_read_b64_tr_b16 v[248:249], v151 offset:0x3c00
	s_waitcnt lgkmcnt(6)
	v_mfma_f32_32x32x16_bf16 v[16:31], v[2:5], v[134:137], v[16:31]
	ds_read_b64_tr_b16 v[134:135], v151 offset:0x600
	ds_read_b64_tr_b16 v[136:137], v151 offset:0xe00
	s_waitcnt lgkmcnt(6)
	v_mfma_f32_32x32x16_bf16 v[16:31], v[88:91], v[138:141], v[16:31]
	ds_read_b64_tr_b16 v[138:139], v151 offset:0x1600
	ds_read_b64_tr_b16 v[140:141], v151 offset:0x1e00
	s_waitcnt lgkmcnt(6)
	v_mfma_f32_32x32x16_bf16 v[16:31], v[92:95], v[142:145], v[16:31]
	ds_read_b64_tr_b16 v[142:143], v151 offset:0x2600
	ds_read_b64_tr_b16 v[144:145], v151 offset:0x2e00
	s_waitcnt lgkmcnt(6)
	v_mfma_f32_32x32x16_bf16 v[16:31], v[130:133], v[246:249], v[16:31]
	ds_read_b64_tr_b16 v[246:247], v151 offset:0x3600
	ds_read_b64_tr_b16 v[248:249], v151 offset:0x3e00
	s_waitcnt lgkmcnt(0)
	v_mfma_f32_32x32x16_bf16 v[48:63], v[2:5], v[134:137], v[48:63]
	v_max_f32_e32 v2, v96, v96
	v_max_f32_e32 v3, v14, v14
	v_max_f32_e32 v2, v3, v2
	v_max3_f32 v2, v2, v243, v244
	v_max3_f32 v2, v2, v115, v245
	v_max3_f32 v2, v2, v117, v118
	v_max3_f32 v2, v2, v119, v120
	v_max3_f32 v2, v2, v121, v122
	v_max3_f32 v2, v2, v123, v124
	v_mfma_f32_32x32x16_bf16 v[48:63], v[88:91], v[138:141], v[48:63]
	v_max3_f32 v2, v2, v125, v126
	v_max3_f32 v2, v2, v0, v15
	v_max3_f32 v2, v2, v97, v98
	v_max3_f32 v2, v2, v99, v100
	v_max3_f32 v2, v2, v101, v102
	v_max3_f32 v2, v2, v103, v104
	v_max3_f32 v2, v2, v105, v106
	v_max3_f32 v2, v2, v107, v108
	v_mfma_f32_32x32x16_bf16 v[48:63], v[92:95], v[142:145], v[48:63]
	v_max3_f32 v2, v2, v109, v110
	v_mov_b32_e32 v3, v2
	s_nop 1
	v_permlane32_swap_b32_e32 v2, v3
	v_max_f32_e32 v3, v3, v3
	v_max_f32_e32 v2, v2, v2
	v_max_f32_e32 v2, v2, v3
	v_sub_f32_e32 v3, v2, v237
	s_mov_b32 s36, 0x42b504f3
	v_cmp_ge_f32_e32 vcc, s36, v3
	v_max_f32_e32 v3, v237, v237
	v_max_f32_e32 v2, v3, v2
	v_mfma_f32_32x32x16_bf16 v[48:63], v[130:133], v[246:249], v[48:63]
	v_sub_f32_e32 v3, v237, v2
	v_mul_f32_e32 v3, 0x3e0293ee, v3
	v_exp_f32_e32 v3, v3
	s_cmp_eq_u64 vcc, exec
	s_cselect_b64 s[36:37], -1, 0
	s_waitcnt vmcnt(0)
	v_cndmask_b32_e64 v114, v3, 1.0, s[36:37]
	v_cmp_gt_f32_e32 vcc, 1.0, v114
	v_mov_b64_e32 v[168:169], v[6:7]
	v_mov_b64_e32 v[170:171], v[8:9]
	v_mov_b64_e32 v[194:195], v[84:85]
	v_mov_b64_e32 v[196:197], v[86:87]
	ds_write_b128 v156, v[10:13] offset:32768
	ds_write_b128 v157, v[80:83] offset:32768
	s_cbranch_vccz .LBB0_517
	s_mov_b64 s[48:49], exec
	v_readlane_b32 s52, v255, 58
	v_readlane_b32 s53, v255, 59
	s_and_b64 s[52:53], s[48:49], s[52:53]
	s_mov_b64 exec, s[52:53]
	ds_write_b32 v148, v114 offset:128
	s_or_b64 exec, exec, s[48:49]
	s_waitcnt lgkmcnt(0)
	ds_read_b128 v[4:7], v146 offset:128
	ds_read_b128 v[8:11], v146 offset:160
	ds_read_b128 v[80:83], v146 offset:192
	ds_read_b128 v[84:87], v146 offset:224
	s_waitcnt lgkmcnt(3)
	v_pk_mul_f32 v[64:65], v[4:5], v[64:65]
	v_pk_mul_f32 v[66:67], v[66:67], v[6:7]
	s_waitcnt lgkmcnt(2)
	v_pk_mul_f32 v[68:69], v[68:69], v[8:9]
	v_pk_mul_f32 v[70:71], v[70:71], v[10:11]
	s_waitcnt lgkmcnt(1)
	v_pk_mul_f32 v[72:73], v[72:73], v[80:81]
	v_pk_mul_f32 v[74:75], v[74:75], v[82:83]
	s_waitcnt lgkmcnt(0)
	v_pk_mul_f32 v[76:77], v[76:77], v[84:85]
	v_pk_mul_f32 v[46:47], v[46:47], v[86:87]
	v_pk_mul_f32 v[42:43], v[42:43], v[82:83]
	v_pk_mul_f32 v[38:39], v[38:39], v[10:11]
	v_pk_mul_f32 v[34:35], v[34:35], v[6:7]
	v_pk_mul_f32 v[44:45], v[44:45], v[84:85]
	v_pk_mul_f32 v[40:41], v[40:41], v[80:81]
	v_pk_mul_f32 v[36:37], v[36:37], v[8:9]
	v_pk_mul_f32 v[32:33], v[32:33], v[4:5]
	v_pk_mul_f32 v[78:79], v[78:79], v[86:87]
	v_pk_mul_f32 v[48:49], v[4:5], v[48:49]
	v_pk_mul_f32 v[50:51], v[50:51], v[6:7]
	v_pk_mul_f32 v[52:53], v[52:53], v[8:9]
	v_pk_mul_f32 v[54:55], v[54:55], v[10:11]
	v_pk_mul_f32 v[56:57], v[56:57], v[80:81]
	v_pk_mul_f32 v[58:59], v[58:59], v[82:83]
	v_pk_mul_f32 v[60:61], v[60:61], v[84:85]
	v_pk_mul_f32 v[30:31], v[30:31], v[86:87]
	v_pk_mul_f32 v[26:27], v[26:27], v[82:83]
	v_pk_mul_f32 v[22:23], v[22:23], v[10:11]
	v_pk_mul_f32 v[18:19], v[18:19], v[6:7]
	v_pk_mul_f32 v[28:29], v[28:29], v[84:85]
	v_pk_mul_f32 v[24:25], v[24:25], v[80:81]
	v_pk_mul_f32 v[20:21], v[20:21], v[8:9]
	v_pk_mul_f32 v[16:17], v[16:17], v[4:5]
	v_pk_mul_f32 v[62:63], v[62:63], v[86:87]

; #define SBAR() __builtin_amdgcn_sched_barrier(0)
; __device__ __forceinline__ void finishSM(f32x16& p0, f32x16& p1, float alpha, float& l_reg, bf16x8& pa0, bf16x8& pa1, bf16x8& pa2, bf16x8& pa3) {
; #pragma unroll
;   for (int r = 0; r < 16; ++r) p1[r] = __builtin_amdgcn_exp2f(p1[r]);
;   float ps = 0;
; #pragma unroll
;   for (int r = 0; r < 16; ++r) ps += p0[r];
; #pragma unroll
;   for (int r = 0; r < 16; ++r) ps += p1[r];
;   { auto rr = __builtin_amdgcn_permlane32_swap(__float_as_uint(ps), __float_as_uint(ps), false, false);
;     ps = __uint_as_float(rr[0]) + __uint_as_float(rr[1]); }
;   l_reg = l_reg * alpha + ps;
;     ...
;   PK4(p0, 0, pa0); PK4(p0, 8, pa1); PK4(p1, 0, pa2); PK4(p1, 8, pa3);
;     ...
; }
; template <int D0> __device__ __forceinline__ void pv_one(f32x16& od, int vb, bf16x8 pa0, bf16x8 pa1, bf16x8 pa2, bf16x8 pa3) {
;   const s16x4 l0 = tr_read<v_rd_off(D0, 0, 0)>(vb), h0 = tr_read<v_rd_off(D0, 0, 1)>(vb), l1 = tr_read<v_rd_off(D0, 1, 0)>(vb), h1 = tr_read<v_rd_off(D0, 1, 1)>(vb);
;   const s16x4 l2 = tr_read<v_rd_off(D0, 2, 0)>(vb), h2 = tr_read<v_rd_off(D0, 2, 1)>(vb), l3 = tr_read<v_rd_off(D0, 3, 0)>(vb), h3 = tr_read<v_rd_off(D0, 3, 1)>(vb);
;   asm volatile("s_waitcnt lgkmcnt(0)" ::: "memory"); SBAR();
;     ...
;   od = __builtin_amdgcn_mfma_f32_32x32x16_bf16(pa0, PK(l0, h0), od, 0, 0, 0);
;   od = __builtin_amdgcn_mfma_f32_32x32x16_bf16(pa1, PK(l1, h1), od, 0, 0, 0);
;   od = __builtin_amdgcn_mfma_f32_32x32x16_bf16(pa2, PK(l2, h2), od, 0, 0, 0);
;   od = __builtin_amdgcn_mfma_f32_32x32x16_bf16(pa3, PK(l3, h3), od, 0, 0, 0);
;     ...
; }
; __device__ __forceinline__ void pv_d0(f32x16* o, int vb, bf16x8 pa0, bf16x8 pa1, bf16x8 pa2, bf16x8 pa3) {
;   pv_one<0>(o[0], vb, pa0, pa1, pa2, pa3); pv_one<1>(o[1], vb, pa0, pa1, pa2, pa3); pv_one<2>(o[2], vb, pa0, pa1, pa2, pa3); pv_one<3>(o[3], vb, pa0, pa1, pa2, pa3);
.LBB0_581:
	s_or_b64 exec, exec, s[36:37]
	v_add_f32_e32 v110, 0, v121
	v_add_f32_e32 v110, v123, v110
	v_add_f32_e32 v110, v12, v110
	v_add_f32_e32 v110, v122, v110
	v_add_f32_e32 v110, v10, v110
	v_add_f32_e32 v110, v13, v110
	v_add_f32_e32 v110, v9, v110
	v_add_f32_e32 v110, v11, v110
	v_add_f32_e32 v110, v6, v110
	v_add_f32_e32 v110, v8, v110
	v_add_f32_e32 v110, v4, v110
	v_add_f32_e32 v110, v7, v110
	v_exp_f32_e32 v80, v124
	v_add_f32_e32 v110, v2, v110
	v_exp_f32_e32 v81, v125
	v_add_f32_e32 v110, v5, v110
	v_exp_f32_e32 v82, v126
	v_add_f32_e32 v110, v0, v110
	v_exp_f32_e32 v83, v130
	v_add_f32_e32 v110, v3, v110
	v_exp_f32_e32 v95, v131
	v_add_f32_e32 v110, v80, v110
	v_exp_f32_e32 v142, v132
	v_add_f32_e32 v110, v81, v110
	v_exp_f32_e32 v143, v133
	v_add_f32_e32 v110, v82, v110
	v_exp_f32_e32 v144, v134
	v_add_f32_e32 v110, v83, v110
	v_exp_f32_e32 v145, v135
	v_add_f32_e32 v110, v95, v110
	v_exp_f32_e32 v164, v136
	v_add_f32_e32 v110, v142, v110
	v_exp_f32_e32 v165, v137
	v_add_f32_e32 v110, v143, v110
	v_exp_f32_e32 v166, v138
	v_add_f32_e32 v110, v144, v110
	v_exp_f32_e32 v167, v139
	v_add_f32_e32 v110, v145, v110
	v_exp_f32_e32 v140, v140
	v_add_f32_e32 v110, v164, v110
	v_exp_f32_e32 v141, v141
	v_add_f32_e32 v110, v165, v110
	v_exp_f32_e32 v172, v127
	v_add_f32_e32 v110, v166, v110
	v_add_f32_e32 v110, v167, v110
	v_add_f32_e32 v110, v140, v110
	v_add_f32_e32 v110, v141, v110
	v_add_f32_e32 v110, v172, v110
	v_mov_b32_e32 v111, v110
	s_nop 1
	v_permlane32_swap_b32_e32 v110, v111
	v_cvt_pk_bf16_f32 v124, v121, v123
	v_cvt_pk_bf16_f32 v125, v12, v122
	v_cvt_pk_bf16_f32 v126, v10, v13
	v_cvt_pk_bf16_f32 v127, v9, v11
	v_cvt_pk_bf16_f32 v130, v6, v8
	v_cvt_pk_bf16_f32 v131, v4, v7
	v_cvt_pk_bf16_f32 v132, v2, v5
	v_cvt_pk_bf16_f32 v133, v0, v3
	v_cvt_pk_bf16_f32 v134, v80, v81
	v_cvt_pk_bf16_f32 v135, v82, v83
	v_cvt_pk_bf16_f32 v136, v95, v142
	v_cvt_pk_bf16_f32 v137, v143, v144
	v_cvt_pk_bf16_f32 v138, v145, v164
	v_cvt_pk_bf16_f32 v139, v165, v166
	v_cvt_pk_bf16_f32 v140, v167, v140
	v_cvt_pk_bf16_f32 v141, v141, v172
	s_nop 0
	v_permlane32_swap_b32_e32 v124, v126
	v_permlane32_swap_b32_e32 v125, v127
	v_permlane32_swap_b32_e32 v130, v132
	v_permlane32_swap_b32_e32 v131, v133
	v_permlane32_swap_b32_e32 v134, v136
	v_permlane32_swap_b32_e32 v135, v137
	v_permlane32_swap_b32_e32 v138, v140
	v_permlane32_swap_b32_e32 v139, v141
	s_mov_b32 s36, 0xa0000
	v_add_co_u32_e32 v6, vcc, s36, v128
	s_mov_b32 s36, 0xf0000
	s_nop 0
	v_addc_co_u32_e32 v7, vcc, 0, v129, vcc
	v_add_co_u32_e32 v10, vcc, s36, v128
	s_nop 1
	v_addc_co_u32_e32 v11, vcc, 0, v129, vcc
	global_load_dwordx4 v[2:5], v[6:7], off offset:1024
	s_nop 0
	global_load_dwordx4 v[6:9], v[6:7], off
	s_nop 0
	global_load_dwordx4 v[80:83], v[10:11], off offset:1024
	s_nop 0
	global_load_dwordx4 v[10:13], v[10:11], off
	ds_read_b64_tr_b16 v[142:143], v149 offset:0
	ds_read_b64_tr_b16 v[144:145], v149 offset:0x800
	ds_read_b64_tr_b16 v[164:165], v149 offset:0x1000
	ds_read_b64_tr_b16 v[166:167], v149 offset:0x1800
	ds_read_b64_tr_b16 v[244:245], v149 offset:0x2000
	ds_read_b64_tr_b16 v[246:247], v149 offset:0x2800
	ds_read_b64_tr_b16 v[172:173], v149 offset:0x3000
	ds_read_b64_tr_b16 v[174:175], v149 offset:0x3800
	s_waitcnt lgkmcnt(0)
	s_nop 0
	v_mfma_f32_32x32x16_bf16 v[32:47], v[124:127], v[142:145], v[32:47]
	ds_read_b64_tr_b16 v[142:143], v149 offset:0x200
	ds_read_b64_tr_b16 v[144:145], v149 offset:0xa00
	v_mfma_f32_32x32x16_bf16 v[32:47], v[130:133], v[164:167], v[32:47]
	ds_read_b64_tr_b16 v[164:165], v149 offset:0x1200
	ds_read_b64_tr_b16 v[166:167], v149 offset:0x1a00
	v_mfma_f32_32x32x16_bf16 v[32:47], v[134:137], v[244:247], v[32:47]
	v_mfma_f32_32x32x16_bf16 v[32:47], v[138:141], v[172:175], v[32:47]
	ds_read_b64_tr_b16 v[172:173], v149 offset:0x2200
	ds_read_b64_tr_b16 v[174:175], v149 offset:0x2a00
	ds_read_b64_tr_b16 v[244:245], v149 offset:0x3200
	ds_read_b64_tr_b16 v[246:247], v149 offset:0x3a00
	s_waitcnt lgkmcnt(6)
	v_mfma_f32_32x32x16_bf16 v[64:79], v[124:127], v[142:145], v[64:79]
	ds_read_b64_tr_b16 v[142:143], v149 offset:0x400
	ds_read_b64_tr_b16 v[144:145], v149 offset:0xc00
	s_waitcnt lgkmcnt(6)
	v_mfma_f32_32x32x16_bf16 v[64:79], v[130:133], v[164:167], v[64:79]
	ds_read_b64_tr_b16 v[164:165], v149 offset:0x1400
	ds_read_b64_tr_b16 v[166:167], v149 offset:0x1c00
	s_waitcnt lgkmcnt(6)
	v_mfma_f32_32x32x16_bf16 v[64:79], v[134:137], v[172:175], v[64:79]
	ds_read_b64_tr_b16 v[172:173], v149 offset:0x2400
	ds_read_b64_tr_b16 v[174:175], v149 offset:0x2c00
	s_waitcnt lgkmcnt(6)
; #define SBAR() __builtin_amdgcn_sched_barrier(0)
; __device__ __forceinline__ void partialSM(f32x16& p0, f32x16& p1, float& m_reg, float& mn, float& alpha, float C, float thrRaw) {
;   float pmax = p0[0];
; #pragma unroll
;   for (int r = 1; r < 16; ++r) pmax = fmaxf(pmax, p0[r]);
; #pragma unroll
;   for (int r = 0; r < 16; ++r) pmax = fmaxf(pmax, p1[r]);
;   { auto rr = __builtin_amdgcn_permlane32_swap(__float_as_uint(pmax), __float_as_uint(pmax), false, false);
;     pmax = fmaxf(__uint_as_float(rr[0]), __uint_as_float(rr[1])); }
;   if (__builtin_expect(__all(pmax - m_reg <= thrRaw), 1)) { mn = m_reg; alpha = 1.f; }
;   else { mn = fmaxf(m_reg, pmax); alpha = __builtin_amdgcn_exp2f((m_reg - mn) * C); m_reg = mn; }
; template <int D0> __device__ __forceinline__ void pv_one(f32x16& od, int vb, bf16x8 pa0, bf16x8 pa1, bf16x8 pa2, bf16x8 pa3) {
;   const s16x4 l0 = tr_read<v_rd_off(D0, 0, 0)>(vb), h0 = tr_read<v_rd_off(D0, 0, 1)>(vb), l1 = tr_read<v_rd_off(D0, 1, 0)>(vb), h1 = tr_read<v_rd_off(D0, 1, 1)>(vb);
;   const s16x4 l2 = tr_read<v_rd_off(D0, 2, 0)>(vb), h2 = tr_read<v_rd_off(D0, 2, 1)>(vb), l3 = tr_read<v_rd_off(D0, 3, 0)>(vb), h3 = tr_read<v_rd_off(D0, 3, 1)>(vb);
;   asm volatile("s_waitcnt lgkmcnt(0)" ::: "memory"); SBAR();
;     ...
;   od = __builtin_amdgcn_mfma_f32_32x32x16_bf16(pa0, PK(l0, h0), od, 0, 0, 0);
;   od = __builtin_amdgcn_mfma_f32_32x32x16_bf16(pa1, PK(l1, h1), od, 0, 0, 0);
;   od = __builtin_amdgcn_mfma_f32_32x32x16_bf16(pa2, PK(l2, h2), od, 0, 0, 0);
;   od = __builtin_amdgcn_mfma_f32_32x32x16_bf16(pa3, PK(l3, h3), od, 0, 0, 0);
;     ...
; }
; __device__ __forceinline__ void pv_d0(f32x16* o, int vb, bf16x8 pa0, bf16x8 pa1, bf16x8 pa2, bf16x8 pa3) {
;   pv_one<0>(o[0], vb, pa0, pa1, pa2, pa3); pv_one<1>(o[1], vb, pa0, pa1, pa2, pa3); pv_one<2>(o[2], vb, pa0, pa1, pa2, pa3); pv_one<3>(o[3], vb, pa0, pa1, pa2, pa3);
	v_mfma_f32_32x32x16_bf16 v[64:79], v[138:141], v[244:247], v[64:79]
	ds_read_b64_tr_b16 v[244:245], v149 offset:0x3400
	ds_read_b64_tr_b16 v[246:247], v149 offset:0x3c00
	s_waitcnt lgkmcnt(6)
	v_mfma_f32_32x32x16_bf16 v[16:31], v[124:127], v[142:145], v[16:31]
	ds_read_b64_tr_b16 v[142:143], v149 offset:0x600
	ds_read_b64_tr_b16 v[144:145], v149 offset:0xe00
	s_waitcnt lgkmcnt(6)
	v_mfma_f32_32x32x16_bf16 v[16:31], v[130:133], v[164:167], v[16:31]
	ds_read_b64_tr_b16 v[164:165], v149 offset:0x1600
	ds_read_b64_tr_b16 v[166:167], v149 offset:0x1e00
	s_waitcnt lgkmcnt(6)
	v_mfma_f32_32x32x16_bf16 v[16:31], v[134:137], v[172:175], v[16:31]
	ds_read_b64_tr_b16 v[172:173], v149 offset:0x2600
	ds_read_b64_tr_b16 v[174:175], v149 offset:0x2e00
	s_waitcnt lgkmcnt(6)
	v_mfma_f32_32x32x16_bf16 v[16:31], v[138:141], v[244:247], v[16:31]
	ds_read_b64_tr_b16 v[244:245], v149 offset:0x3600
	ds_read_b64_tr_b16 v[246:247], v149 offset:0x3e00
	s_waitcnt lgkmcnt(0)
	v_mfma_f32_32x32x16_bf16 v[48:63], v[124:127], v[142:145], v[48:63]
	v_max_f32_e32 v0, v117, v117
	v_max_f32_e32 v95, v115, v115
	v_max_f32_e32 v0, v95, v0
	v_max3_f32 v0, v0, v118, v119
	v_max3_f32 v0, v0, v120, v100
	v_max3_f32 v0, v0, v101, v102
	v_max3_f32 v0, v0, v103, v104
	v_max3_f32 v0, v0, v105, v106
	v_max3_f32 v0, v0, v107, v108
	v_mfma_f32_32x32x16_bf16 v[48:63], v[130:133], v[164:167], v[48:63]
	v_max3_f32 v0, v0, v109, v94
	v_max3_f32 v0, v0, v14, v15
	v_max3_f32 v0, v0, v96, v97
	v_max3_f32 v0, v0, v98, v99
	v_max3_f32 v0, v0, v84, v85
	v_max3_f32 v0, v0, v86, v87
	v_max3_f32 v0, v0, v88, v89
	v_max3_f32 v0, v0, v90, v91
	v_mfma_f32_32x32x16_bf16 v[48:63], v[134:137], v[172:175], v[48:63]
	v_max3_f32 v0, v0, v92, v93
	v_mov_b32_e32 v95, v0
	s_nop 1
	v_permlane32_swap_b32_e32 v0, v95
	v_max_f32_e32 v95, v95, v95
	v_max_f32_e32 v0, v0, v0
	v_max_f32_e32 v0, v0, v95
	v_sub_f32_e32 v95, v0, v116
	s_mov_b32 s36, 0x42b504f3
	v_cmp_ge_f32_e32 vcc, s36, v95
	v_max_f32_e32 v95, v116, v116
	v_max_f32_e32 v95, v95, v0
	v_mfma_f32_32x32x16_bf16 v[48:63], v[138:141], v[244:247], v[48:63]
	v_sub_f32_e32 v0, v116, v95
	v_mul_f32_e32 v0, 0x3e0293ee, v0
	v_exp_f32_e32 v0, v0
	s_cmp_eq_u64 vcc, exec
	s_cselect_b64 s[36:37], -1, 0
	s_waitcnt vmcnt(0)
	v_cndmask_b32_e64 v0, v0, 1.0, s[36:37]
	v_cmp_gt_f32_e32 vcc, 1.0, v0
	v_mov_b64_e32 v[168:169], v[2:3]
	v_mov_b64_e32 v[170:171], v[4:5]
	v_mov_b64_e32 v[194:195], v[80:81]
	v_mov_b64_e32 v[196:197], v[82:83]
	ds_write_b128 v156, v[6:9] offset:49152
	ds_write_b128 v157, v[10:13] offset:49152
	s_cbranch_vccz .LBB0_585
	s_mov_b64 s[48:49], exec
	v_readlane_b32 s50, v255, 58
	v_readlane_b32 s51, v255, 59
	s_and_b64 s[50:51], s[48:49], s[50:51]
	s_mov_b64 exec, s[50:51]
	ds_write_b32 v148, v0 offset:128
	s_or_b64 exec, exec, s[48:49]
	s_waitcnt lgkmcnt(0)
	ds_read_b128 v[2:5], v146 offset:128
	ds_read_b128 v[6:9], v146 offset:160
	ds_read_b128 v[10:13], v146 offset:192
	ds_read_b128 v[80:83], v146 offset:224
	s_waitcnt lgkmcnt(3)
	v_pk_mul_f32 v[64:65], v[2:3], v[64:65]
	v_pk_mul_f32 v[66:67], v[66:67], v[4:5]
	s_waitcnt lgkmcnt(2)
	v_pk_mul_f32 v[68:69], v[68:69], v[6:7]
	v_pk_mul_f32 v[70:71], v[70:71], v[8:9]
	s_waitcnt lgkmcnt(1)
	v_pk_mul_f32 v[72:73], v[72:73], v[10:11]
	v_pk_mul_f32 v[74:75], v[74:75], v[12:13]
	s_waitcnt lgkmcnt(0)
	v_pk_mul_f32 v[76:77], v[76:77], v[80:81]
	v_pk_mul_f32 v[46:47], v[46:47], v[82:83]
	v_pk_mul_f32 v[42:43], v[42:43], v[12:13]
	v_pk_mul_f32 v[38:39], v[38:39], v[8:9]
	v_pk_mul_f32 v[34:35], v[34:35], v[4:5]
	v_pk_mul_f32 v[44:45], v[44:45], v[80:81]
	v_pk_mul_f32 v[40:41], v[40:41], v[10:11]
	v_pk_mul_f32 v[36:37], v[36:37], v[6:7]
	v_pk_mul_f32 v[32:33], v[32:33], v[2:3]
	v_pk_mul_f32 v[78:79], v[78:79], v[82:83]
	v_pk_mul_f32 v[48:49], v[2:3], v[48:49]
	v_pk_mul_f32 v[50:51], v[50:51], v[4:5]
	v_pk_mul_f32 v[52:53], v[52:53], v[6:7]
	v_pk_mul_f32 v[54:55], v[54:55], v[8:9]
	v_pk_mul_f32 v[56:57], v[56:57], v[10:11]
	v_pk_mul_f32 v[58:59], v[58:59], v[12:13]
	v_pk_mul_f32 v[60:61], v[60:61], v[80:81]
	v_pk_mul_f32 v[30:31], v[30:31], v[82:83]
	v_pk_mul_f32 v[26:27], v[26:27], v[12:13]
	v_pk_mul_f32 v[22:23], v[22:23], v[8:9]
	v_pk_mul_f32 v[18:19], v[18:19], v[4:5]
	v_pk_mul_f32 v[28:29], v[28:29], v[80:81]
	v_pk_mul_f32 v[24:25], v[24:25], v[10:11]
	v_pk_mul_f32 v[20:21], v[20:21], v[6:7]
	v_pk_mul_f32 v[16:17], v[16:17], v[2:3]
	v_pk_mul_f32 v[62:63], v[62:63], v[82:83]

; __device__ __forceinline__ void finishSM(f32x16& p0, f32x16& p1, float alpha, float& l_reg, bf16x8& pa0, bf16x8& pa1, bf16x8& pa2, bf16x8& pa3) {
; #pragma unroll
;   for (int r = 0; r < 16; ++r) p1[r] = __builtin_amdgcn_exp2f(p1[r]);
;   float ps = 0;
; #pragma unroll
;   for (int r = 0; r < 16; ++r) ps += p0[r];
; #pragma unroll
;   for (int r = 0; r < 16; ++r) ps += p1[r];
;   { auto rr = __builtin_amdgcn_permlane32_swap(__float_as_uint(ps), __float_as_uint(ps), false, false);
;     ps = __uint_as_float(rr[0]) + __uint_as_float(rr[1]); }
;   l_reg = l_reg * alpha + ps;
;     ...
;   PK4(p0, 0, pa0); PK4(p0, 8, pa1); PK4(p1, 0, pa2); PK4(p1, 8, pa3);
; template <int DK, bool QL>
; __device__ __forceinline__ void qkt(f32x16& p0, f32x16& p1, const bf16* Ks, const bf16x8* qr, const char* ql, int r32, int hi) {
;   p0 = f32x16{}; p1 = f32x16{};
; #pragma unroll
;   for (int d0 = 0; d0 < DK / 16; ++d0) { int cb = (d0 * 16 + hi * 8) * 2;
;     const bf16x8 qv = QL ? *reinterpret_cast<const bf16x8*>(ql + d0 * 1024) : qr[d0];
;     bf16x8 b0 = *reinterpret_cast<const bf16x8*>((const char*)Ks + kswz<DK>(r32, cb));
;     bf16x8 b1 = *reinterpret_cast<const bf16x8*>((const char*)Ks + kswz<DK>(32 + r32, cb));
;     p0 = __builtin_amdgcn_mfma_f32_32x32x16_bf16(b0, qv, p0, 0, 0, 0);
;     p1 = __builtin_amdgcn_mfma_f32_32x32x16_bf16(b1, qv, p1, 0, 0, 0); }
.LBB0_660:
	ds_read_b128 v[66:69], v153
	ds_read_b128 v[70:73], v159 offset:49152
	ds_read_b128 v[74:77], v159 offset:57344
	ds_read_b128 v[218:221], v153 offset:1024
	ds_read_b128 v[222:225], v207 offset:49152
	ds_read_b128 v[226:229], v207 offset:57344
	v_add_f32_e32 v130, 0, v145
	v_add_f32_e32 v130, v216, v130
	s_waitcnt lgkmcnt(4)
	v_mfma_f32_32x32x16_bf16 v[82:97], v[70:73], v[66:69], 0
	v_add_f32_e32 v130, v131, v130
	v_add_f32_e32 v130, v215, v130
	v_add_f32_e32 v130, v132, v130
	v_add_f32_e32 v130, v144, v130
	v_add_f32_e32 v130, v133, v130
	v_add_f32_e32 v130, v143, v130
	v_add_f32_e32 v130, v140, v130
	s_waitcnt lgkmcnt(3)
	v_mfma_f32_32x32x16_bf16 v[66:81], v[74:77], v[66:69], 0
	v_add_f32_e32 v130, v142, v130
	v_add_f32_e32 v130, v139, v130
	v_add_f32_e32 v130, v141, v130
	v_exp_f32_e32 v126, v126
	v_add_f32_e32 v130, v136, v130
	v_exp_f32_e32 v127, v127
	v_add_f32_e32 v130, v138, v130
	s_waitcnt lgkmcnt(1)
	v_mfma_f32_32x32x16_bf16 v[82:97], v[222:225], v[218:221], v[82:97]
	v_exp_f32_e32 v124, v124
	v_add_f32_e32 v130, v135, v130
	v_exp_f32_e32 v125, v125
	v_add_f32_e32 v130, v137, v130
	v_exp_f32_e32 v118, v118
	v_add_f32_e32 v130, v126, v130
	v_exp_f32_e32 v119, v119
	s_waitcnt lgkmcnt(0)
	v_mfma_f32_32x32x16_bf16 v[66:81], v[226:229], v[218:221], v[66:81]
	ds_read_b128 v[218:221], v153 offset:2048
	ds_read_b128 v[222:225], v161 offset:49152
	ds_read_b128 v[226:229], v161 offset:57344
	v_add_f32_e32 v130, v127, v130
	v_exp_f32_e32 v116, v116
	v_add_f32_e32 v130, v124, v130
	v_exp_f32_e32 v117, v117
	v_add_f32_e32 v130, v125, v130
	v_exp_f32_e32 v114, v114
	s_waitcnt lgkmcnt(1)
	v_mfma_f32_32x32x16_bf16 v[82:97], v[222:225], v[218:221], v[82:97]
	v_add_f32_e32 v130, v118, v130
	v_exp_f32_e32 v115, v115
	v_add_f32_e32 v130, v119, v130
	v_exp_f32_e32 v128, v128
	v_add_f32_e32 v130, v116, v130
	v_exp_f32_e32 v129, v129
	v_add_f32_e32 v130, v117, v130
	s_waitcnt lgkmcnt(0)
	v_mfma_f32_32x32x16_bf16 v[66:81], v[226:229], v[218:221], v[66:81]
	ds_read_b128 v[218:221], v153 offset:3072
	ds_read_b128 v[222:225], v160 offset:49152
	ds_read_b128 v[226:229], v160 offset:57344
	v_exp_f32_e32 v122, v122
	v_add_f32_e32 v130, v114, v130
	v_exp_f32_e32 v123, v123
	v_add_f32_e32 v130, v115, v130
	v_exp_f32_e32 v120, v120
	v_add_f32_e32 v130, v128, v130
	s_waitcnt lgkmcnt(1)
	v_mfma_f32_32x32x16_bf16 v[82:97], v[222:225], v[218:221], v[82:97]
	v_exp_f32_e32 v121, v121
	v_add_f32_e32 v130, v129, v130
	v_add_f32_e32 v130, v122, v130
	v_add_f32_e32 v130, v123, v130
	v_add_f32_e32 v130, v120, v130
	v_add_f32_e32 v212, v121, v130
	v_mov_b32_e32 v213, v212
	s_waitcnt lgkmcnt(0)
	v_mfma_f32_32x32x16_bf16 v[66:81], v[226:229], v[218:221], v[66:81]
	ds_read_b128 v[218:221], v153 offset:4096
	ds_read_b128 v[222:225], v158 offset:49152
	ds_read_b128 v[226:229], v158 offset:57344
	v_permlane32_swap_b32_e32 v212, v213
	s_waitcnt lgkmcnt(1)
	v_mfma_f32_32x32x16_bf16 v[82:97], v[222:225], v[218:221], v[82:97]
	s_waitcnt lgkmcnt(0)
	v_mfma_f32_32x32x16_bf16 v[66:81], v[226:229], v[218:221], v[66:81]
	ds_read_b128 v[218:221], v153 offset:5120
	ds_read_b128 v[222:225], v156 offset:49152
	ds_read_b128 v[226:229], v156 offset:57344
	s_waitcnt lgkmcnt(1)
	v_mfma_f32_32x32x16_bf16 v[82:97], v[222:225], v[218:221], v[82:97]
	s_waitcnt lgkmcnt(0)
	v_mfma_f32_32x32x16_bf16 v[66:81], v[226:229], v[218:221], v[66:81]
	ds_read_b128 v[218:221], v153 offset:6144
	ds_read_b128 v[222:225], v157 offset:49152
	ds_read_b128 v[226:229], v157 offset:57344
	s_waitcnt lgkmcnt(1)
	v_mfma_f32_32x32x16_bf16 v[82:97], v[222:225], v[218:221], v[82:97]
	s_waitcnt lgkmcnt(0)
	v_mfma_f32_32x32x16_bf16 v[66:81], v[226:229], v[218:221], v[66:81]
	ds_read_b128 v[218:221], v153 offset:7168
	ds_read_b128 v[222:225], v176 offset:49152
	ds_read_b128 v[226:229], v176 offset:57344
	v_cvt_pk_bf16_f32 v130, v145, v216
	v_cvt_pk_bf16_f32 v131, v131, v215
	v_cvt_pk_bf16_f32 v132, v132, v144
	v_cvt_pk_bf16_f32 v133, v133, v143
	v_cvt_pk_bf16_f32 v140, v140, v142
	v_cvt_pk_bf16_f32 v141, v139, v141
	s_waitcnt lgkmcnt(1)
	v_mfma_f32_32x32x16_bf16 v[82:97], v[222:225], v[218:221], v[82:97]
	v_cvt_pk_bf16_f32 v142, v136, v138
	v_cvt_pk_bf16_f32 v143, v135, v137
	v_cvt_pk_bf16_f32 v136, v126, v127
	v_cvt_pk_bf16_f32 v137, v124, v125
	v_cvt_pk_bf16_f32 v138, v118, v119
	v_cvt_pk_bf16_f32 v139, v116, v117
	v_cvt_pk_bf16_f32 v214, v114, v115
	s_waitcnt lgkmcnt(0)
	v_mfma_f32_32x32x16_bf16 v[66:81], v[226:229], v[218:221], v[66:81]
	v_cvt_pk_bf16_f32 v215, v128, v129
	v_cvt_pk_bf16_f32 v216, v122, v123
	v_permlane32_swap_b32_e32 v130, v132
	v_cvt_pk_bf16_f32 v217, v120, v121
	v_permlane32_swap_b32_e32 v214, v216
	v_permlane32_swap_b32_e32 v131, v133
	v_permlane32_swap_b32_e32 v140, v142
	v_permlane32_swap_b32_e32 v141, v143
	v_permlane32_swap_b32_e32 v136, v138
	v_permlane32_swap_b32_e32 v137, v139
	v_permlane32_swap_b32_e32 v215, v217
	s_mov_b32 s2, 0xfff10000
	v_add_co_u32_e32 v118, vcc, s2, v146
	s_mov_b32 s2, 0xfff60000
	s_nop 0
	v_addc_co_u32_e32 v119, vcc, -1, v147, vcc
	v_add_co_u32_e32 v122, vcc, s2, v146
	s_nop 1
	v_addc_co_u32_e32 v123, vcc, -1, v147, vcc
	global_load_dwordx4 v[114:117], v[118:119], off
	s_nop 0
	global_load_dwordx4 v[118:121], v[118:119], off offset:-512
	s_nop 0
	global_load_dwordx4 v[126:129], v[122:123], off
	s_nop 0
	global_load_dwordx4 v[122:125], v[122:123], off offset:-512
	ds_read_b64_tr_b16 v[218:219], v152 offset:0
	ds_read_b64_tr_b16 v[220:221], v152 offset:0x800
	ds_read_b64_tr_b16 v[222:223], v152 offset:0x1000
	ds_read_b64_tr_b16 v[224:225], v152 offset:0x1800
	ds_read_b64_tr_b16 v[226:227], v152 offset:0x2000
	ds_read_b64_tr_b16 v[228:229], v152 offset:0x2800
	ds_read_b64_tr_b16 v[230:231], v152 offset:0x3000
	ds_read_b64_tr_b16 v[232:233], v152 offset:0x3800
	s_waitcnt lgkmcnt(6)
; #define SBAR() __builtin_amdgcn_sched_barrier(0)
; template <int D0> __device__ __forceinline__ void pv_one(f32x16& od, int vb, bf16x8 pa0, bf16x8 pa1, bf16x8 pa2, bf16x8 pa3) {
;   const s16x4 l0 = tr_read<v_rd_off(D0, 0, 0)>(vb), h0 = tr_read<v_rd_off(D0, 0, 1)>(vb), l1 = tr_read<v_rd_off(D0, 1, 0)>(vb), h1 = tr_read<v_rd_off(D0, 1, 1)>(vb);
;   const s16x4 l2 = tr_read<v_rd_off(D0, 2, 0)>(vb), h2 = tr_read<v_rd_off(D0, 2, 1)>(vb), l3 = tr_read<v_rd_off(D0, 3, 0)>(vb), h3 = tr_read<v_rd_off(D0, 3, 1)>(vb);
;   asm volatile("s_waitcnt lgkmcnt(0)" ::: "memory"); SBAR();
;     ...
;   od = __builtin_amdgcn_mfma_f32_32x32x16_bf16(pa0, PK(l0, h0), od, 0, 0, 0);
;   od = __builtin_amdgcn_mfma_f32_32x32x16_bf16(pa1, PK(l1, h1), od, 0, 0, 0);
;   od = __builtin_amdgcn_mfma_f32_32x32x16_bf16(pa2, PK(l2, h2), od, 0, 0, 0);
;   od = __builtin_amdgcn_mfma_f32_32x32x16_bf16(pa3, PK(l3, h3), od, 0, 0, 0);
;     ...
; }
; __device__ __forceinline__ void pv_d0(f32x16* o, int vb, bf16x8 pa0, bf16x8 pa1, bf16x8 pa2, bf16x8 pa3) {
;   pv_one<0>(o[0], vb, pa0, pa1, pa2, pa3); pv_one<1>(o[1], vb, pa0, pa1, pa2, pa3); pv_one<2>(o[2], vb, pa0, pa1, pa2, pa3); pv_one<3>(o[3], vb, pa0, pa1, pa2, pa3);
	s_nop 0
	v_mfma_f32_32x32x16_bf16 v[18:33], v[130:133], v[218:221], v[18:33]
	ds_read_b64_tr_b16 v[218:219], v152 offset:0x200
	ds_read_b64_tr_b16 v[220:221], v152 offset:0xa00
	s_waitcnt lgkmcnt(6)
	v_mfma_f32_32x32x16_bf16 v[18:33], v[140:143], v[222:225], v[18:33]
	ds_read_b64_tr_b16 v[222:223], v152 offset:0x1200
	ds_read_b64_tr_b16 v[224:225], v152 offset:0x1a00
	s_waitcnt lgkmcnt(6)
	v_mfma_f32_32x32x16_bf16 v[18:33], v[136:139], v[226:229], v[18:33]
	ds_read_b64_tr_b16 v[226:227], v152 offset:0x2200
	ds_read_b64_tr_b16 v[228:229], v152 offset:0x2a00
	s_waitcnt lgkmcnt(6)
	v_mfma_f32_32x32x16_bf16 v[18:33], v[214:217], v[230:233], v[18:33]
	ds_read_b64_tr_b16 v[230:231], v152 offset:0x3200
	ds_read_b64_tr_b16 v[232:233], v152 offset:0x3a00
	s_waitcnt lgkmcnt(6)
	v_mfma_f32_32x32x16_bf16 v[50:65], v[130:133], v[218:221], v[50:65]
	ds_read_b64_tr_b16 v[218:219], v152 offset:0x400
	ds_read_b64_tr_b16 v[220:221], v152 offset:0xc00
	s_waitcnt lgkmcnt(6)
	v_mfma_f32_32x32x16_bf16 v[50:65], v[140:143], v[222:225], v[50:65]
	ds_read_b64_tr_b16 v[222:223], v152 offset:0x1400
	ds_read_b64_tr_b16 v[224:225], v152 offset:0x1c00
	s_waitcnt lgkmcnt(6)
	v_mfma_f32_32x32x16_bf16 v[50:65], v[136:139], v[226:229], v[50:65]
	ds_read_b64_tr_b16 v[226:227], v152 offset:0x2400
	ds_read_b64_tr_b16 v[228:229], v152 offset:0x2c00
	s_waitcnt lgkmcnt(6)
	v_mfma_f32_32x32x16_bf16 v[50:65], v[214:217], v[230:233], v[50:65]
	ds_read_b64_tr_b16 v[230:231], v152 offset:0x3400
	ds_read_b64_tr_b16 v[232:233], v152 offset:0x3c00
	s_waitcnt lgkmcnt(6)
	v_mfma_f32_32x32x16_bf16 v[2:17], v[130:133], v[218:221], v[2:17]
	ds_read_b64_tr_b16 v[218:219], v152 offset:0x600
	ds_read_b64_tr_b16 v[220:221], v152 offset:0xe00
	s_waitcnt lgkmcnt(6)
	v_mfma_f32_32x32x16_bf16 v[2:17], v[140:143], v[222:225], v[2:17]
	ds_read_b64_tr_b16 v[222:223], v152 offset:0x1600
	ds_read_b64_tr_b16 v[224:225], v152 offset:0x1e00
	s_waitcnt lgkmcnt(6)
	v_mfma_f32_32x32x16_bf16 v[2:17], v[136:139], v[226:229], v[2:17]
	ds_read_b64_tr_b16 v[226:227], v152 offset:0x2600
	ds_read_b64_tr_b16 v[228:229], v152 offset:0x2e00
	s_waitcnt lgkmcnt(6)
	v_mfma_f32_32x32x16_bf16 v[2:17], v[214:217], v[230:233], v[2:17]
	ds_read_b64_tr_b16 v[230:231], v152 offset:0x3600
	ds_read_b64_tr_b16 v[232:233], v152 offset:0x3e00
	s_waitcnt lgkmcnt(0)
	v_mfma_f32_32x32x16_bf16 v[34:49], v[130:133], v[218:221], v[34:49]
	v_max_f32_e32 v130, v83, v83
	v_max_f32_e32 v131, v82, v82
	v_max_f32_e32 v130, v131, v130
	v_max3_f32 v130, v130, v84, v85
	v_max3_f32 v130, v130, v86, v87
	v_max3_f32 v130, v130, v88, v89
	v_max3_f32 v130, v130, v90, v91
	v_max3_f32 v130, v130, v92, v93
	v_max3_f32 v130, v130, v94, v95
	v_mfma_f32_32x32x16_bf16 v[34:49], v[140:143], v[222:225], v[34:49]
	v_max3_f32 v130, v130, v96, v97
	v_max3_f32 v130, v130, v66, v67
	v_max3_f32 v130, v130, v68, v69
	v_max3_f32 v130, v130, v70, v71
	v_max3_f32 v130, v130, v72, v73
	v_max3_f32 v130, v130, v74, v75
	v_max3_f32 v130, v130, v76, v77
	v_max3_f32 v130, v130, v78, v79
	v_mfma_f32_32x32x16_bf16 v[34:49], v[136:139], v[226:229], v[34:49]
	v_max3_f32 v130, v130, v80, v81
	v_mov_b32_e32 v131, v130
	s_nop 1
	v_permlane32_swap_b32_e32 v130, v131
	v_max_f32_e32 v131, v131, v131
	v_max_f32_e32 v130, v130, v130
	v_max_f32_e32 v130, v130, v131
	v_sub_f32_e32 v131, v130, v134
	s_mov_b32 s2, 0x42b504f3
	v_cmp_ge_f32_e32 vcc, s2, v131
	v_max_f32_e32 v131, v134, v134
	v_max_f32_e32 v130, v131, v130
	v_mfma_f32_32x32x16_bf16 v[34:49], v[214:217], v[230:233], v[34:49]
	v_sub_f32_e32 v131, v134, v130
	v_mul_f32_e32 v131, 0x3e0293ee, v131
	v_exp_f32_e32 v131, v131
	s_cmp_eq_u64 vcc, exec
	s_cselect_b64 s[2:3], -1, 0
	s_waitcnt vmcnt(4)
	v_cndmask_b32_e64 v214, v131, 1.0, s[2:3]
	v_cmp_gt_f32_e32 vcc, 1.0, v214
	s_waitcnt vmcnt(4)
	ds_write_b128 v177, v[98:101] offset:32768
	ds_write_b128 v208, v[102:105] offset:32768
	s_cbranch_vccz .LBB0_664
	s_and_saveexec_b64 s[4:5], s[0:1]
	ds_write_b32 v149, v214 offset:128
	s_or_b64 exec, exec, s[4:5]
	s_waitcnt lgkmcnt(0)
	v_add_u32_e32 v131, v148, v0
	ds_read_b128 v[136:139], v131 offset:128
	ds_read_b128 v[140:143], v131 offset:160
	ds_read_b128 v[216:219], v131 offset:192
	ds_read_b128 v[220:223], v131 offset:224
	s_waitcnt lgkmcnt(3)
	v_pk_mul_f32 v[50:51], v[136:137], v[50:51]
	v_pk_mul_f32 v[52:53], v[52:53], v[138:139]
	s_waitcnt lgkmcnt(2)
	v_pk_mul_f32 v[54:55], v[54:55], v[140:141]
	v_pk_mul_f32 v[56:57], v[56:57], v[142:143]
	s_waitcnt lgkmcnt(1)
	v_pk_mul_f32 v[58:59], v[58:59], v[216:217]
	v_pk_mul_f32 v[60:61], v[60:61], v[218:219]
	s_waitcnt lgkmcnt(0)
	v_pk_mul_f32 v[62:63], v[62:63], v[220:221]
	v_pk_mul_f32 v[30:31], v[30:31], v[220:221]
	v_pk_mul_f32 v[26:27], v[26:27], v[216:217]
	v_pk_mul_f32 v[22:23], v[22:23], v[140:141]
	v_pk_mul_f32 v[32:33], v[32:33], v[222:223]
	v_pk_mul_f32 v[28:29], v[28:29], v[218:219]
	v_pk_mul_f32 v[24:25], v[24:25], v[142:143]
	v_pk_mul_f32 v[20:21], v[20:21], v[138:139]
	v_pk_mul_f32 v[18:19], v[18:19], v[136:137]
	v_pk_mul_f32 v[64:65], v[64:65], v[222:223]
	v_pk_mul_f32 v[34:35], v[136:137], v[34:35]
	v_pk_mul_f32 v[36:37], v[36:37], v[138:139]
	v_pk_mul_f32 v[38:39], v[38:39], v[140:141]
	v_pk_mul_f32 v[40:41], v[40:41], v[142:143]
	v_pk_mul_f32 v[42:43], v[42:43], v[216:217]
	v_pk_mul_f32 v[44:45], v[44:45], v[218:219]
	v_pk_mul_f32 v[46:47], v[46:47], v[220:221]
	v_pk_mul_f32 v[14:15], v[14:15], v[220:221]
	v_pk_mul_f32 v[10:11], v[10:11], v[216:217]
	v_pk_mul_f32 v[6:7], v[6:7], v[140:141]
	v_pk_mul_f32 v[16:17], v[16:17], v[222:223]
	v_pk_mul_f32 v[12:13], v[12:13], v[218:219]
	v_pk_mul_f32 v[8:9], v[8:9], v[142:143]
	v_pk_mul_f32 v[4:5], v[4:5], v[138:139]
	v_pk_mul_f32 v[2:3], v[2:3], v[136:137]
	v_pk_mul_f32 v[48:49], v[48:49], v[222:223]

; #define SBAR() __builtin_amdgcn_sched_barrier(0)
; template <int D0> __device__ __forceinline__ void pv_one(f32x16& od, int vb, bf16x8 pa0, bf16x8 pa1, bf16x8 pa2, bf16x8 pa3) {
;   const s16x4 l0 = tr_read<v_rd_off(D0, 0, 0)>(vb), h0 = tr_read<v_rd_off(D0, 0, 1)>(vb), l1 = tr_read<v_rd_off(D0, 1, 0)>(vb), h1 = tr_read<v_rd_off(D0, 1, 1)>(vb);
;   const s16x4 l2 = tr_read<v_rd_off(D0, 2, 0)>(vb), h2 = tr_read<v_rd_off(D0, 2, 1)>(vb), l3 = tr_read<v_rd_off(D0, 3, 0)>(vb), h3 = tr_read<v_rd_off(D0, 3, 1)>(vb);
;   asm volatile("s_waitcnt lgkmcnt(0)" ::: "memory"); SBAR();
;     ...
;   od = __builtin_amdgcn_mfma_f32_32x32x16_bf16(pa0, PK(l0, h0), od, 0, 0, 0);
;   od = __builtin_amdgcn_mfma_f32_32x32x16_bf16(pa1, PK(l1, h1), od, 0, 0, 0);
;   od = __builtin_amdgcn_mfma_f32_32x32x16_bf16(pa2, PK(l2, h2), od, 0, 0, 0);
;   od = __builtin_amdgcn_mfma_f32_32x32x16_bf16(pa3, PK(l3, h3), od, 0, 0, 0);
;     ...
; }
; __device__ __forceinline__ void pv_d0(f32x16* o, int vb, bf16x8 pa0, bf16x8 pa1, bf16x8 pa2, bf16x8 pa3) {
;   pv_one<0>(o[0], vb, pa0, pa1, pa2, pa3); pv_one<1>(o[1], vb, pa0, pa1, pa2, pa3); pv_one<2>(o[2], vb, pa0, pa1, pa2, pa3); pv_one<3>(o[3], vb, pa0, pa1, pa2, pa3);
.LBB0_666:
	ds_read_b64_tr_b16 v[220:221], v151 offset:0
	ds_read_b64_tr_b16 v[222:223], v151 offset:0x800
	ds_read_b64_tr_b16 v[224:225], v151 offset:0x1000
	ds_read_b64_tr_b16 v[226:227], v151 offset:0x1800
	ds_read_b64_tr_b16 v[228:229], v151 offset:0x2000
	ds_read_b64_tr_b16 v[230:231], v151 offset:0x2800
	ds_read_b64_tr_b16 v[232:233], v151 offset:0x3000
	ds_read_b64_tr_b16 v[234:235], v151 offset:0x3800
	s_waitcnt lgkmcnt(6)
	s_nop 0
	v_mfma_f32_32x32x16_bf16 v[18:33], v[130:133], v[220:223], v[18:33]
	ds_read_b64_tr_b16 v[220:221], v151 offset:0x200
	ds_read_b64_tr_b16 v[222:223], v151 offset:0xa00
	s_waitcnt lgkmcnt(6)
	v_mfma_f32_32x32x16_bf16 v[18:33], v[134:137], v[224:227], v[18:33]
	ds_read_b64_tr_b16 v[224:225], v151 offset:0x1200
	ds_read_b64_tr_b16 v[226:227], v151 offset:0x1a00
	s_waitcnt lgkmcnt(6)
	v_mfma_f32_32x32x16_bf16 v[18:33], v[138:141], v[228:231], v[18:33]
	ds_read_b64_tr_b16 v[228:229], v151 offset:0x2200
	ds_read_b64_tr_b16 v[230:231], v151 offset:0x2a00
	s_waitcnt lgkmcnt(6)
	v_mfma_f32_32x32x16_bf16 v[18:33], v[142:145], v[232:235], v[18:33]
	ds_read_b64_tr_b16 v[232:233], v151 offset:0x3200
	ds_read_b64_tr_b16 v[234:235], v151 offset:0x3a00
	s_waitcnt lgkmcnt(6)
	v_mfma_f32_32x32x16_bf16 v[50:65], v[130:133], v[220:223], v[50:65]
	ds_read_b64_tr_b16 v[220:221], v151 offset:0x400
	ds_read_b64_tr_b16 v[222:223], v151 offset:0xc00
	s_waitcnt lgkmcnt(6)
	v_mfma_f32_32x32x16_bf16 v[50:65], v[134:137], v[224:227], v[50:65]
	ds_read_b64_tr_b16 v[224:225], v151 offset:0x1400
	ds_read_b64_tr_b16 v[226:227], v151 offset:0x1c00
	s_waitcnt lgkmcnt(6)
	v_mfma_f32_32x32x16_bf16 v[50:65], v[138:141], v[228:231], v[50:65]
	ds_read_b64_tr_b16 v[228:229], v151 offset:0x2400
	ds_read_b64_tr_b16 v[230:231], v151 offset:0x2c00
	s_waitcnt lgkmcnt(6)
	v_mfma_f32_32x32x16_bf16 v[50:65], v[142:145], v[232:235], v[50:65]
	ds_read_b64_tr_b16 v[232:233], v151 offset:0x3400
	ds_read_b64_tr_b16 v[234:235], v151 offset:0x3c00
	s_waitcnt lgkmcnt(6)
	v_mfma_f32_32x32x16_bf16 v[2:17], v[130:133], v[220:223], v[2:17]
	ds_read_b64_tr_b16 v[220:221], v151 offset:0x600
	ds_read_b64_tr_b16 v[222:223], v151 offset:0xe00
	s_waitcnt lgkmcnt(6)
	v_mfma_f32_32x32x16_bf16 v[2:17], v[134:137], v[224:227], v[2:17]
	ds_read_b64_tr_b16 v[224:225], v151 offset:0x1600
	ds_read_b64_tr_b16 v[226:227], v151 offset:0x1e00
	s_waitcnt lgkmcnt(6)
	v_mfma_f32_32x32x16_bf16 v[2:17], v[138:141], v[228:231], v[2:17]
	ds_read_b64_tr_b16 v[228:229], v151 offset:0x2600
	ds_read_b64_tr_b16 v[230:231], v151 offset:0x2e00
	s_waitcnt lgkmcnt(6)
	v_mfma_f32_32x32x16_bf16 v[2:17], v[142:145], v[232:235], v[2:17]
	ds_read_b64_tr_b16 v[232:233], v151 offset:0x3600
	ds_read_b64_tr_b16 v[234:235], v151 offset:0x3e00
	s_waitcnt lgkmcnt(0)
	v_mfma_f32_32x32x16_bf16 v[34:49], v[130:133], v[220:223], v[34:49]
	v_max_f32_e32 v130, v83, v83
	v_max_f32_e32 v131, v82, v82
	v_max_f32_e32 v130, v131, v130
	v_max3_f32 v130, v130, v84, v85
	v_max3_f32 v130, v130, v86, v87
	v_max3_f32 v130, v130, v88, v89
	v_max3_f32 v130, v130, v90, v91
	v_max3_f32 v130, v130, v92, v93
	v_max3_f32 v130, v130, v94, v95
	v_mfma_f32_32x32x16_bf16 v[34:49], v[134:137], v[224:227], v[34:49]
	v_max3_f32 v130, v130, v96, v97
	v_max3_f32 v130, v130, v66, v67
	v_max3_f32 v130, v130, v68, v69
	v_max3_f32 v130, v130, v70, v71
	v_max3_f32 v130, v130, v72, v73
	v_max3_f32 v130, v130, v74, v75
	v_max3_f32 v130, v130, v76, v77
	v_max3_f32 v130, v130, v78, v79
	v_mfma_f32_32x32x16_bf16 v[34:49], v[138:141], v[228:231], v[34:49]
	v_max3_f32 v130, v130, v80, v81
	v_mov_b32_e32 v131, v130
	s_nop 1
	v_permlane32_swap_b32_e32 v130, v131
	v_max_f32_e32 v131, v131, v131
	v_max_f32_e32 v130, v130, v130
	v_max_f32_e32 v130, v130, v131
	v_sub_f32_e32 v131, v130, v215
	s_mov_b32 s2, 0x42b504f3
	v_cmp_ge_f32_e32 vcc, s2, v131
	v_max_f32_e32 v131, v215, v215
	v_max_f32_e32 v131, v131, v130
	v_mfma_f32_32x32x16_bf16 v[34:49], v[142:145], v[232:235], v[34:49]
	v_sub_f32_e32 v130, v215, v131
	v_mul_f32_e32 v130, 0x3e0293ee, v130
	v_exp_f32_e32 v130, v130
	s_cmp_eq_u64 vcc, exec
	s_cselect_b64 s[2:3], -1, 0
	s_waitcnt vmcnt(4)
	v_cndmask_b32_e64 v130, v130, 1.0, s[2:3]
	v_cmp_gt_f32_e32 vcc, 1.0, v130
	v_mov_b64_e32 v[244:245], v[114:115]
	v_mov_b64_e32 v[246:247], v[116:117]
	v_mov_b64_e32 v[194:195], v[126:127]
	v_mov_b64_e32 v[196:197], v[128:129]
	ds_write_b128 v177, v[118:121] offset:49152
	ds_write_b128 v208, v[122:125] offset:49152
	s_cbranch_vccz .LBB0_670
	s_and_saveexec_b64 s[6:7], s[0:1]
	ds_write_b32 v149, v130 offset:128
	s_or_b64 exec, exec, s[6:7]
	s_waitcnt lgkmcnt(0)
	v_add_u32_e32 v126, v148, v0
	ds_read_b128 v[114:117], v126 offset:128
	ds_read_b128 v[118:121], v126 offset:160
	ds_read_b128 v[122:125], v126 offset:192
	ds_read_b128 v[126:129], v126 offset:224
	s_waitcnt lgkmcnt(3)
	v_pk_mul_f32 v[50:51], v[114:115], v[50:51]
	v_pk_mul_f32 v[52:53], v[52:53], v[116:117]
	s_waitcnt lgkmcnt(2)
	v_pk_mul_f32 v[54:55], v[54:55], v[118:119]
	v_pk_mul_f32 v[56:57], v[56:57], v[120:121]
	s_waitcnt lgkmcnt(1)
	v_pk_mul_f32 v[58:59], v[58:59], v[122:123]
	v_pk_mul_f32 v[60:61], v[60:61], v[124:125]
	s_waitcnt lgkmcnt(0)
	v_pk_mul_f32 v[62:63], v[62:63], v[126:127]
	v_pk_mul_f32 v[30:31], v[30:31], v[126:127]
	v_pk_mul_f32 v[26:27], v[26:27], v[122:123]
	v_pk_mul_f32 v[22:23], v[22:23], v[118:119]
	v_pk_mul_f32 v[32:33], v[32:33], v[128:129]
	v_pk_mul_f32 v[28:29], v[28:29], v[124:125]
	v_pk_mul_f32 v[24:25], v[24:25], v[120:121]
	v_pk_mul_f32 v[20:21], v[20:21], v[116:117]
	v_pk_mul_f32 v[18:19], v[18:19], v[114:115]
	v_pk_mul_f32 v[64:65], v[64:65], v[128:129]
	v_pk_mul_f32 v[34:35], v[114:115], v[34:35]
	v_pk_mul_f32 v[36:37], v[36:37], v[116:117]
	v_pk_mul_f32 v[38:39], v[38:39], v[118:119]
	v_pk_mul_f32 v[40:41], v[40:41], v[120:121]
	v_pk_mul_f32 v[42:43], v[42:43], v[122:123]
	v_pk_mul_f32 v[44:45], v[44:45], v[124:125]
	v_pk_mul_f32 v[46:47], v[46:47], v[126:127]
	v_pk_mul_f32 v[14:15], v[14:15], v[126:127]
	v_pk_mul_f32 v[10:11], v[10:11], v[122:123]
	v_pk_mul_f32 v[6:7], v[6:7], v[118:119]
	v_pk_mul_f32 v[16:17], v[16:17], v[128:129]
	v_pk_mul_f32 v[12:13], v[12:13], v[124:125]
	v_pk_mul_f32 v[8:9], v[8:9], v[120:121]
	v_pk_mul_f32 v[4:5], v[4:5], v[116:117]
	v_pk_mul_f32 v[2:3], v[2:3], v[114:115]
	v_pk_mul_f32 v[48:49], v[48:49], v[128:129]

; __device__ __forceinline__ void finishSM(f32x16& p0, f32x16& p1, float alpha, float& l_reg, bf16x8& pa0, bf16x8& pa1, bf16x8& pa2, bf16x8& pa3) {
; #pragma unroll
;   for (int r = 0; r < 16; ++r) p1[r] = __builtin_amdgcn_exp2f(p1[r]);
;   float ps = 0;
; #pragma unroll
;   for (int r = 0; r < 16; ++r) ps += p0[r];
; #pragma unroll
;   for (int r = 0; r < 16; ++r) ps += p1[r];
;   { auto rr = __builtin_amdgcn_permlane32_swap(__float_as_uint(ps), __float_as_uint(ps), false, false);
;     ps = __uint_as_float(rr[0]) + __uint_as_float(rr[1]); }
;   l_reg = l_reg * alpha + ps;
;     ...
;   PK4(p0, 0, pa0); PK4(p0, 8, pa1); PK4(p1, 0, pa2); PK4(p1, 8, pa3);
; template <int DK, bool QL>
; __device__ __forceinline__ void qkt(f32x16& p0, f32x16& p1, const bf16* Ks, const bf16x8* qr, const char* ql, int r32, int hi) {
;   p0 = f32x16{}; p1 = f32x16{};
; #pragma unroll
;   for (int d0 = 0; d0 < DK / 16; ++d0) { int cb = (d0 * 16 + hi * 8) * 2;
;     const bf16x8 qv = QL ? *reinterpret_cast<const bf16x8*>(ql + d0 * 1024) : qr[d0];
;     bf16x8 b0 = *reinterpret_cast<const bf16x8*>((const char*)Ks + kswz<DK>(r32, cb));
;     bf16x8 b1 = *reinterpret_cast<const bf16x8*>((const char*)Ks + kswz<DK>(32 + r32, cb));
;     p0 = __builtin_amdgcn_mfma_f32_32x32x16_bf16(b0, qv, p0, 0, 0, 0);
;     p1 = __builtin_amdgcn_mfma_f32_32x32x16_bf16(b1, qv, p1, 0, 0, 0); }
.LBB0_682:
	ds_read_b128 v[66:69], v212 offset:49152
	ds_read_b128 v[70:73], v212 offset:53248
	v_exp_f32_e32 v143, v138
	v_add_f32_e32 v138, 0, v177
	v_add_f32_e32 v138, v226, v138
	s_waitcnt lgkmcnt(1)
	v_mfma_f32_32x32x16_bf16 v[82:97], v[66:69], v[110:113], 0
	v_add_f32_e32 v138, v161, v138
	v_add_f32_e32 v138, v223, v138
	v_add_f32_e32 v138, v153, v138
	ds_read_b128 v[228:231], v216 offset:49152
	ds_read_b128 v[232:235], v216 offset:53248
	v_add_f32_e32 v138, v176, v138
	v_add_f32_e32 v138, v152, v138
	v_add_f32_e32 v138, v160, v138
	s_waitcnt lgkmcnt(2)
	v_mfma_f32_32x32x16_bf16 v[66:81], v[70:73], v[110:113], 0
	v_add_f32_e32 v138, v149, v138
	v_add_f32_e32 v138, v151, v138
	v_add_f32_e32 v138, v147, v138
	v_add_f32_e32 v138, v150, v138
	v_add_f32_e32 v138, v145, v138
	v_exp_f32_e32 v164, v139
	v_add_f32_e32 v138, v148, v138
	s_waitcnt lgkmcnt(1)
	v_mfma_f32_32x32x16_bf16 v[82:97], v[228:231], v[106:109], v[82:97]
	v_exp_f32_e32 v136, v136
	v_add_f32_e32 v138, v144, v138
	v_exp_f32_e32 v137, v137
	v_add_f32_e32 v138, v146, v138
	v_exp_f32_e32 v130, v130
	v_add_f32_e32 v138, v143, v138
	v_exp_f32_e32 v131, v131
	s_waitcnt lgkmcnt(0)
	v_mfma_f32_32x32x16_bf16 v[66:81], v[232:235], v[106:109], v[66:81]
	ds_read_b128 v[228:231], v217 offset:49152
	ds_read_b128 v[232:235], v217 offset:53248
	v_add_f32_e32 v138, v164, v138
	v_exp_f32_e32 v128, v128
	v_add_f32_e32 v138, v136, v138
	v_exp_f32_e32 v129, v129
	v_add_f32_e32 v138, v137, v138
	v_exp_f32_e32 v126, v126
	s_waitcnt lgkmcnt(1)
	v_mfma_f32_32x32x16_bf16 v[82:97], v[228:231], v[98:101], v[82:97]
	v_add_f32_e32 v138, v130, v138
	v_exp_f32_e32 v127, v127
	v_add_f32_e32 v138, v131, v138
	v_exp_f32_e32 v165, v140
	v_add_f32_e32 v138, v128, v138
	v_exp_f32_e32 v166, v141
	v_add_f32_e32 v138, v129, v138
	s_waitcnt lgkmcnt(0)
	v_mfma_f32_32x32x16_bf16 v[66:81], v[232:235], v[98:101], v[66:81]
	ds_read_b128 v[228:231], v218 offset:49152
	ds_read_b128 v[232:235], v218 offset:53248
	v_exp_f32_e32 v134, v134
	v_add_f32_e32 v138, v126, v138
	v_exp_f32_e32 v135, v135
	v_add_f32_e32 v138, v127, v138
	v_exp_f32_e32 v132, v132
	v_add_f32_e32 v138, v165, v138
	s_waitcnt lgkmcnt(1)
	v_mfma_f32_32x32x16_bf16 v[82:97], v[228:231], v[102:105], v[82:97]
	v_exp_f32_e32 v133, v133
	v_add_f32_e32 v138, v166, v138
	v_add_f32_e32 v138, v134, v138
	v_add_f32_e32 v138, v135, v138
	v_add_f32_e32 v138, v132, v138
	v_add_f32_e32 v220, v133, v138
	v_mov_b32_e32 v221, v220
	s_waitcnt lgkmcnt(0)
	v_mfma_f32_32x32x16_bf16 v[66:81], v[232:235], v[102:105], v[66:81]
	v_cvt_pk_bf16_f32 v138, v177, v226
	v_cvt_pk_bf16_f32 v139, v161, v223
	v_cvt_pk_bf16_f32 v140, v153, v176
	v_cvt_pk_bf16_f32 v141, v152, v160
	v_cvt_pk_bf16_f32 v222, v149, v151
	v_cvt_pk_bf16_f32 v223, v147, v150
	v_cvt_pk_bf16_f32 v224, v145, v148
	v_permlane32_swap_b32_e32 v220, v221
	v_permlane32_swap_b32_e32 v138, v140
	v_cvt_pk_bf16_f32 v225, v144, v146
	v_permlane32_swap_b32_e32 v222, v224
	v_cvt_pk_bf16_f32 v144, v143, v164
	v_cvt_pk_bf16_f32 v145, v136, v137
	v_cvt_pk_bf16_f32 v146, v130, v131
	v_cvt_pk_bf16_f32 v147, v128, v129
	v_cvt_pk_bf16_f32 v148, v126, v127
	v_cvt_pk_bf16_f32 v149, v165, v166
	v_cvt_pk_bf16_f32 v150, v134, v135
	v_cvt_pk_bf16_f32 v151, v132, v133
	v_permlane32_swap_b32_e32 v139, v141
	v_permlane32_swap_b32_e32 v223, v225
	v_permlane32_swap_b32_e32 v144, v146
	v_permlane32_swap_b32_e32 v145, v147
	v_permlane32_swap_b32_e32 v148, v150
	v_permlane32_swap_b32_e32 v149, v151
	v_readlane_b32 s2, v254, 32
	v_readlane_b32 s3, v254, 33
	s_mov_b32 s4, 0xe0e0000
	s_mov_b32 s5, 0xe130000
	v_lshl_add_u64 v[160:161], v[156:157], 0, s[2:3]
	v_add_co_u32_e32 v126, vcc, s4, v160
	v_lshl_add_u64 v[176:177], v[158:159], 0, s[2:3]
	s_nop 0
	v_addc_co_u32_e32 v127, vcc, 0, v161, vcc
	v_add_co_u32_e32 v130, vcc, s5, v160
	s_nop 1
	v_addc_co_u32_e32 v131, vcc, 0, v161, vcc
	v_add_co_u32_e32 v134, vcc, s4, v176
	global_load_dwordx4 v[126:129], v[126:127], off offset:2048
	s_nop 0
	global_load_dwordx4 v[130:133], v[130:131], off offset:2048
	v_addc_co_u32_e32 v135, vcc, 0, v177, vcc
	global_load_dwordx4 v[134:137], v[134:135], off offset:1024
	ds_read_b64_tr_b16 v[226:227], v211 offset:0
	ds_read_b64_tr_b16 v[228:229], v211 offset:0x800
	ds_read_b64_tr_b16 v[230:231], v211 offset:0x1000
	ds_read_b64_tr_b16 v[232:233], v211 offset:0x1800
	ds_read_b64_tr_b16 v[234:235], v211 offset:0x2000
	ds_read_b64_tr_b16 v[236:237], v211 offset:0x2800
	ds_read_b64_tr_b16 v[238:239], v211 offset:0x3000
	ds_read_b64_tr_b16 v[240:241], v211 offset:0x3800
	s_waitcnt lgkmcnt(6)
	s_nop 0
	v_mfma_f32_32x32x16_bf16 v[18:33], v[138:141], v[226:229], v[18:33]
	ds_read_b64_tr_b16 v[226:227], v211 offset:0x200
	ds_read_b64_tr_b16 v[228:229], v211 offset:0xa00
	s_waitcnt lgkmcnt(6)
	v_mfma_f32_32x32x16_bf16 v[18:33], v[222:225], v[230:233], v[18:33]
	ds_read_b64_tr_b16 v[230:231], v211 offset:0x1200
	ds_read_b64_tr_b16 v[232:233], v211 offset:0x1a00
	s_waitcnt lgkmcnt(6)
	v_mfma_f32_32x32x16_bf16 v[18:33], v[144:147], v[234:237], v[18:33]
	ds_read_b64_tr_b16 v[234:235], v211 offset:0x2200
	ds_read_b64_tr_b16 v[236:237], v211 offset:0x2a00
	s_waitcnt lgkmcnt(6)
; #define SBAR() __builtin_amdgcn_sched_barrier(0)
; template <int D0> __device__ __forceinline__ void pv_one(f32x16& od, int vb, bf16x8 pa0, bf16x8 pa1, bf16x8 pa2, bf16x8 pa3) {
;   const s16x4 l0 = tr_read<v_rd_off(D0, 0, 0)>(vb), h0 = tr_read<v_rd_off(D0, 0, 1)>(vb), l1 = tr_read<v_rd_off(D0, 1, 0)>(vb), h1 = tr_read<v_rd_off(D0, 1, 1)>(vb);
;   const s16x4 l2 = tr_read<v_rd_off(D0, 2, 0)>(vb), h2 = tr_read<v_rd_off(D0, 2, 1)>(vb), l3 = tr_read<v_rd_off(D0, 3, 0)>(vb), h3 = tr_read<v_rd_off(D0, 3, 1)>(vb);
;   asm volatile("s_waitcnt lgkmcnt(0)" ::: "memory"); SBAR();
;     ...
;   od = __builtin_amdgcn_mfma_f32_32x32x16_bf16(pa0, PK(l0, h0), od, 0, 0, 0);
;   od = __builtin_amdgcn_mfma_f32_32x32x16_bf16(pa1, PK(l1, h1), od, 0, 0, 0);
;   od = __builtin_amdgcn_mfma_f32_32x32x16_bf16(pa2, PK(l2, h2), od, 0, 0, 0);
;   od = __builtin_amdgcn_mfma_f32_32x32x16_bf16(pa3, PK(l3, h3), od, 0, 0, 0);
;     ...
; }
; __device__ __forceinline__ void pv_d0(f32x16* o, int vb, bf16x8 pa0, bf16x8 pa1, bf16x8 pa2, bf16x8 pa3) {
;   pv_one<0>(o[0], vb, pa0, pa1, pa2, pa3); pv_one<1>(o[1], vb, pa0, pa1, pa2, pa3); pv_one<2>(o[2], vb, pa0, pa1, pa2, pa3); pv_one<3>(o[3], vb, pa0, pa1, pa2, pa3);
	v_mfma_f32_32x32x16_bf16 v[18:33], v[148:151], v[238:241], v[18:33]
	ds_read_b64_tr_b16 v[238:239], v211 offset:0x3200
	ds_read_b64_tr_b16 v[240:241], v211 offset:0x3a00
	s_waitcnt lgkmcnt(6)
	v_mfma_f32_32x32x16_bf16 v[2:17], v[138:141], v[226:229], v[2:17]
	ds_read_b64_tr_b16 v[226:227], v211 offset:0x400
	ds_read_b64_tr_b16 v[228:229], v211 offset:0xc00
	s_waitcnt lgkmcnt(6)
	v_mfma_f32_32x32x16_bf16 v[2:17], v[222:225], v[230:233], v[2:17]
	ds_read_b64_tr_b16 v[230:231], v211 offset:0x1400
	ds_read_b64_tr_b16 v[232:233], v211 offset:0x1c00
	s_waitcnt lgkmcnt(6)
	v_mfma_f32_32x32x16_bf16 v[2:17], v[144:147], v[234:237], v[2:17]
	ds_read_b64_tr_b16 v[234:235], v211 offset:0x2400
	ds_read_b64_tr_b16 v[236:237], v211 offset:0x2c00
	s_waitcnt lgkmcnt(6)
	v_mfma_f32_32x32x16_bf16 v[2:17], v[148:151], v[238:241], v[2:17]
	ds_read_b64_tr_b16 v[238:239], v211 offset:0x3400
	ds_read_b64_tr_b16 v[240:241], v211 offset:0x3c00
	s_waitcnt lgkmcnt(6)
	v_mfma_f32_32x32x16_bf16 v[50:65], v[138:141], v[226:229], v[50:65]
	ds_read_b64_tr_b16 v[226:227], v211 offset:0x600
	ds_read_b64_tr_b16 v[228:229], v211 offset:0xe00
	s_waitcnt lgkmcnt(6)
	v_mfma_f32_32x32x16_bf16 v[50:65], v[222:225], v[230:233], v[50:65]
	ds_read_b64_tr_b16 v[230:231], v211 offset:0x1600
	ds_read_b64_tr_b16 v[232:233], v211 offset:0x1e00
	s_waitcnt lgkmcnt(6)
	v_mfma_f32_32x32x16_bf16 v[50:65], v[144:147], v[234:237], v[50:65]
	ds_read_b64_tr_b16 v[234:235], v211 offset:0x2600
	ds_read_b64_tr_b16 v[236:237], v211 offset:0x2e00
	s_waitcnt lgkmcnt(6)
	v_mfma_f32_32x32x16_bf16 v[50:65], v[148:151], v[238:241], v[50:65]
	ds_read_b64_tr_b16 v[238:239], v211 offset:0x3600
	ds_read_b64_tr_b16 v[240:241], v211 offset:0x3e00
	s_waitcnt lgkmcnt(0)
	v_mfma_f32_32x32x16_bf16 v[34:49], v[138:141], v[226:229], v[34:49]
	v_max_f32_e32 v138, v83, v83
	v_max_f32_e32 v139, v82, v82
	v_max_f32_e32 v138, v139, v138
	v_max3_f32 v138, v138, v84, v85
	v_max3_f32 v138, v138, v86, v87
	v_max3_f32 v138, v138, v88, v89
	v_max3_f32 v138, v138, v90, v91
	v_max3_f32 v138, v138, v92, v93
	v_max3_f32 v138, v138, v94, v95
	v_mfma_f32_32x32x16_bf16 v[34:49], v[222:225], v[230:233], v[34:49]
	v_max3_f32 v138, v138, v96, v97
	v_max3_f32 v138, v138, v66, v67
	v_max3_f32 v138, v138, v68, v69
	v_max3_f32 v138, v138, v70, v71
	v_max3_f32 v138, v138, v72, v73
	v_max3_f32 v138, v138, v74, v75
	v_max3_f32 v138, v138, v76, v77
	v_max3_f32 v138, v138, v78, v79
	v_mfma_f32_32x32x16_bf16 v[34:49], v[144:147], v[234:237], v[34:49]
	v_max3_f32 v138, v138, v80, v81
	v_mov_b32_e32 v139, v138
	s_nop 1
	v_permlane32_swap_b32_e32 v138, v139
	v_max_f32_e32 v139, v139, v139
	v_max_f32_e32 v138, v138, v138
	v_max_f32_e32 v138, v138, v139
	v_sub_f32_e32 v139, v138, v142
	s_mov_b32 s2, 0x42800000
	v_cmp_ge_f32_e32 vcc, s2, v139
	v_max_f32_e32 v139, v142, v142
	v_max_f32_e32 v138, v139, v138
	v_mfma_f32_32x32x16_bf16 v[34:49], v[148:151], v[238:241], v[34:49]
	v_sub_f32_e32 v139, v142, v138
	v_mul_f32_e32 v139, 0x3e38aa3b, v139
	v_exp_f32_e32 v139, v139
	s_cmp_eq_u64 vcc, exec
	s_cselect_b64 s[2:3], -1, 0
	s_waitcnt vmcnt(3)
	v_cndmask_b32_e64 v222, v139, 1.0, s[2:3]
	v_cmp_gt_f32_e32 vcc, 1.0, v222
	s_waitcnt vmcnt(3)
	ds_write_b128 v213, v[122:125] offset:32768
	s_cbranch_vccz .LBB0_686
	s_and_saveexec_b64 s[4:5], s[0:1]
	ds_write_b32 v208, v222 offset:128
	s_or_b64 exec, exec, s[4:5]
	s_waitcnt lgkmcnt(0)
	v_add_u32_e32 v139, v207, v0
	ds_read_b128 v[144:147], v139 offset:128
	ds_read_b128 v[148:151], v139 offset:160
	ds_read_b128 v[224:227], v139 offset:192
	ds_read_b128 v[228:231], v139 offset:224
	s_waitcnt lgkmcnt(3)
	v_pk_mul_f32 v[2:3], v[144:145], v[2:3]
	v_pk_mul_f32 v[4:5], v[4:5], v[146:147]
	s_waitcnt lgkmcnt(2)
	v_pk_mul_f32 v[6:7], v[6:7], v[148:149]
	v_pk_mul_f32 v[8:9], v[8:9], v[150:151]
	s_waitcnt lgkmcnt(1)
	v_pk_mul_f32 v[10:11], v[10:11], v[224:225]
	v_pk_mul_f32 v[12:13], v[12:13], v[226:227]
	s_waitcnt lgkmcnt(0)
	v_pk_mul_f32 v[14:15], v[14:15], v[228:229]
	v_pk_mul_f32 v[30:31], v[30:31], v[228:229]
	v_pk_mul_f32 v[26:27], v[26:27], v[224:225]
	v_pk_mul_f32 v[22:23], v[22:23], v[148:149]
	v_pk_mul_f32 v[32:33], v[32:33], v[230:231]
	v_pk_mul_f32 v[28:29], v[28:29], v[226:227]
	v_pk_mul_f32 v[24:25], v[24:25], v[150:151]
	v_pk_mul_f32 v[20:21], v[20:21], v[146:147]
	v_pk_mul_f32 v[18:19], v[18:19], v[144:145]
	v_pk_mul_f32 v[16:17], v[16:17], v[230:231]
	v_pk_mul_f32 v[34:35], v[144:145], v[34:35]
	v_pk_mul_f32 v[36:37], v[36:37], v[146:147]
	v_pk_mul_f32 v[38:39], v[38:39], v[148:149]
	v_pk_mul_f32 v[40:41], v[40:41], v[150:151]
	v_pk_mul_f32 v[42:43], v[42:43], v[224:225]
	v_pk_mul_f32 v[44:45], v[44:45], v[226:227]
	v_pk_mul_f32 v[46:47], v[46:47], v[228:229]
	v_pk_mul_f32 v[62:63], v[62:63], v[228:229]
	v_pk_mul_f32 v[58:59], v[58:59], v[224:225]
	v_pk_mul_f32 v[54:55], v[54:55], v[148:149]
	v_pk_mul_f32 v[64:65], v[64:65], v[230:231]
	v_pk_mul_f32 v[60:61], v[60:61], v[226:227]
	v_pk_mul_f32 v[56:57], v[56:57], v[150:151]
	v_pk_mul_f32 v[52:53], v[52:53], v[146:147]
	v_pk_mul_f32 v[50:51], v[50:51], v[144:145]
	v_pk_mul_f32 v[48:49], v[48:49], v[230:231]

; #define SBAR() __builtin_amdgcn_sched_barrier(0)
; template <int D0> __device__ __forceinline__ void pv_one(f32x16& od, int vb, bf16x8 pa0, bf16x8 pa1, bf16x8 pa2, bf16x8 pa3) {
;   const s16x4 l0 = tr_read<v_rd_off(D0, 0, 0)>(vb), h0 = tr_read<v_rd_off(D0, 0, 1)>(vb), l1 = tr_read<v_rd_off(D0, 1, 0)>(vb), h1 = tr_read<v_rd_off(D0, 1, 1)>(vb);
;   const s16x4 l2 = tr_read<v_rd_off(D0, 2, 0)>(vb), h2 = tr_read<v_rd_off(D0, 2, 1)>(vb), l3 = tr_read<v_rd_off(D0, 3, 0)>(vb), h3 = tr_read<v_rd_off(D0, 3, 1)>(vb);
;   asm volatile("s_waitcnt lgkmcnt(0)" ::: "memory"); SBAR();
;     ...
;   od = __builtin_amdgcn_mfma_f32_32x32x16_bf16(pa0, PK(l0, h0), od, 0, 0, 0);
;   od = __builtin_amdgcn_mfma_f32_32x32x16_bf16(pa1, PK(l1, h1), od, 0, 0, 0);
;   od = __builtin_amdgcn_mfma_f32_32x32x16_bf16(pa2, PK(l2, h2), od, 0, 0, 0);
;   od = __builtin_amdgcn_mfma_f32_32x32x16_bf16(pa3, PK(l3, h3), od, 0, 0, 0);
;     ...
; }
; __device__ __forceinline__ void pv_d0(f32x16* o, int vb, bf16x8 pa0, bf16x8 pa1, bf16x8 pa2, bf16x8 pa3) {
;   pv_one<0>(o[0], vb, pa0, pa1, pa2, pa3); pv_one<1>(o[1], vb, pa0, pa1, pa2, pa3); pv_one<2>(o[2], vb, pa0, pa1, pa2, pa3); pv_one<3>(o[3], vb, pa0, pa1, pa2, pa3);
.LBB0_688:
	ds_read_b64_tr_b16 v[226:227], v210 offset:0
	ds_read_b64_tr_b16 v[228:229], v210 offset:0x800
	ds_read_b64_tr_b16 v[230:231], v210 offset:0x1000
	ds_read_b64_tr_b16 v[232:233], v210 offset:0x1800
	ds_read_b64_tr_b16 v[234:235], v210 offset:0x2000
	ds_read_b64_tr_b16 v[236:237], v210 offset:0x2800
	ds_read_b64_tr_b16 v[238:239], v210 offset:0x3000
	ds_read_b64_tr_b16 v[240:241], v210 offset:0x3800
	s_waitcnt lgkmcnt(6)
	s_nop 0
	v_mfma_f32_32x32x16_bf16 v[18:33], v[138:141], v[226:229], v[18:33]
	ds_read_b64_tr_b16 v[226:227], v210 offset:0x200
	ds_read_b64_tr_b16 v[228:229], v210 offset:0xa00
	s_waitcnt lgkmcnt(6)
	v_mfma_f32_32x32x16_bf16 v[18:33], v[142:145], v[230:233], v[18:33]
	ds_read_b64_tr_b16 v[230:231], v210 offset:0x1200
	ds_read_b64_tr_b16 v[232:233], v210 offset:0x1a00
	s_waitcnt lgkmcnt(6)
	v_mfma_f32_32x32x16_bf16 v[18:33], v[146:149], v[234:237], v[18:33]
	ds_read_b64_tr_b16 v[234:235], v210 offset:0x2200
	ds_read_b64_tr_b16 v[236:237], v210 offset:0x2a00
	s_waitcnt lgkmcnt(6)
	v_mfma_f32_32x32x16_bf16 v[18:33], v[150:153], v[238:241], v[18:33]
	ds_read_b64_tr_b16 v[238:239], v210 offset:0x3200
	ds_read_b64_tr_b16 v[240:241], v210 offset:0x3a00
	s_waitcnt lgkmcnt(6)
	v_mfma_f32_32x32x16_bf16 v[2:17], v[138:141], v[226:229], v[2:17]
	ds_read_b64_tr_b16 v[226:227], v210 offset:0x400
	ds_read_b64_tr_b16 v[228:229], v210 offset:0xc00
	s_waitcnt lgkmcnt(6)
	v_mfma_f32_32x32x16_bf16 v[2:17], v[142:145], v[230:233], v[2:17]
	ds_read_b64_tr_b16 v[230:231], v210 offset:0x1400
	ds_read_b64_tr_b16 v[232:233], v210 offset:0x1c00
	s_waitcnt lgkmcnt(6)
	v_mfma_f32_32x32x16_bf16 v[2:17], v[146:149], v[234:237], v[2:17]
	ds_read_b64_tr_b16 v[234:235], v210 offset:0x2400
	ds_read_b64_tr_b16 v[236:237], v210 offset:0x2c00
	s_waitcnt lgkmcnt(6)
	v_mfma_f32_32x32x16_bf16 v[2:17], v[150:153], v[238:241], v[2:17]
	ds_read_b64_tr_b16 v[238:239], v210 offset:0x3400
	ds_read_b64_tr_b16 v[240:241], v210 offset:0x3c00
	s_waitcnt lgkmcnt(6)
	v_mfma_f32_32x32x16_bf16 v[50:65], v[138:141], v[226:229], v[50:65]
	ds_read_b64_tr_b16 v[226:227], v210 offset:0x600
	ds_read_b64_tr_b16 v[228:229], v210 offset:0xe00
	s_waitcnt lgkmcnt(6)
	v_mfma_f32_32x32x16_bf16 v[50:65], v[142:145], v[230:233], v[50:65]
	ds_read_b64_tr_b16 v[230:231], v210 offset:0x1600
	ds_read_b64_tr_b16 v[232:233], v210 offset:0x1e00
	s_waitcnt lgkmcnt(6)
	v_mfma_f32_32x32x16_bf16 v[50:65], v[146:149], v[234:237], v[50:65]
	ds_read_b64_tr_b16 v[234:235], v210 offset:0x2600
	ds_read_b64_tr_b16 v[236:237], v210 offset:0x2e00
	s_waitcnt lgkmcnt(6)
	v_mfma_f32_32x32x16_bf16 v[50:65], v[150:153], v[238:241], v[50:65]
	ds_read_b64_tr_b16 v[238:239], v210 offset:0x3600
	ds_read_b64_tr_b16 v[240:241], v210 offset:0x3e00
	s_waitcnt lgkmcnt(0)
	v_mfma_f32_32x32x16_bf16 v[34:49], v[138:141], v[226:229], v[34:49]
	v_max_f32_e32 v138, v83, v83
	v_max_f32_e32 v139, v82, v82
	v_max_f32_e32 v138, v139, v138
	v_max3_f32 v138, v138, v84, v85
	v_max3_f32 v138, v138, v86, v87
	v_max3_f32 v138, v138, v88, v89
	v_max3_f32 v138, v138, v90, v91
	v_max3_f32 v138, v138, v92, v93
	v_max3_f32 v138, v138, v94, v95
	v_mfma_f32_32x32x16_bf16 v[34:49], v[142:145], v[230:233], v[34:49]
	v_max3_f32 v138, v138, v96, v97
	v_max3_f32 v138, v138, v66, v67
	v_max3_f32 v138, v138, v68, v69
	v_max3_f32 v138, v138, v70, v71
	v_max3_f32 v138, v138, v72, v73
	v_max3_f32 v138, v138, v74, v75
	v_max3_f32 v138, v138, v76, v77
	v_max3_f32 v138, v138, v78, v79
	v_mfma_f32_32x32x16_bf16 v[34:49], v[146:149], v[234:237], v[34:49]
	v_max3_f32 v138, v138, v80, v81
	v_mov_b32_e32 v139, v138
	s_nop 1
	v_permlane32_swap_b32_e32 v138, v139
	v_max_f32_e32 v139, v139, v139
	v_max_f32_e32 v138, v138, v138
	v_max_f32_e32 v138, v138, v139
	v_sub_f32_e32 v139, v138, v223
	s_mov_b32 s2, 0x42800000
	v_cmp_ge_f32_e32 vcc, s2, v139
	v_max_f32_e32 v139, v223, v223
	v_max_f32_e32 v138, v139, v138
	v_mfma_f32_32x32x16_bf16 v[34:49], v[150:153], v[238:241], v[34:49]
	v_sub_f32_e32 v139, v223, v138
	v_mul_f32_e32 v139, 0x3e38aa3b, v139
	v_exp_f32_e32 v139, v139
	s_cmp_eq_u64 vcc, exec
	s_cselect_b64 s[2:3], -1, 0
	s_waitcnt vmcnt(3)
	v_cndmask_b32_e64 v143, v139, 1.0, s[2:3]
	v_cmp_gt_f32_e32 vcc, 1.0, v143
	v_mov_b64_e32 v[182:183], v[126:127]
	v_mov_b64_e32 v[184:185], v[128:129]
	v_mov_b64_e32 v[194:195], v[130:131]
	v_mov_b64_e32 v[196:197], v[132:133]
	ds_write_b128 v213, v[134:137] offset:49152
	s_cbranch_vccz .LBB0_692
	s_and_saveexec_b64 s[6:7], s[0:1]
	ds_write_b32 v208, v143 offset:128
	s_or_b64 exec, exec, s[6:7]
	s_waitcnt lgkmcnt(0)
	v_add_u32_e32 v139, v207, v0
	ds_read_b128 v[126:129], v139 offset:128
	ds_read_b128 v[130:133], v139 offset:160
	ds_read_b128 v[134:137], v139 offset:224
	ds_read_b128 v[144:147], v139 offset:192
	s_waitcnt lgkmcnt(3)
	v_pk_mul_f32 v[50:51], v[126:127], v[50:51]
	v_pk_mul_f32 v[52:53], v[128:129], v[52:53]
	s_waitcnt lgkmcnt(2)
	v_pk_mul_f32 v[54:55], v[130:131], v[54:55]
	s_waitcnt lgkmcnt(1)
	v_pk_mul_f32 v[30:31], v[30:31], v[134:135]
	s_waitcnt lgkmcnt(0)
	v_pk_mul_f32 v[26:27], v[26:27], v[144:145]
	v_pk_mul_f32 v[22:23], v[22:23], v[130:131]
	v_pk_mul_f32 v[32:33], v[32:33], v[136:137]
	v_pk_mul_f32 v[28:29], v[28:29], v[146:147]
	v_pk_mul_f32 v[24:25], v[24:25], v[132:133]
	v_pk_mul_f32 v[20:21], v[20:21], v[128:129]
	v_pk_mul_f32 v[18:19], v[18:19], v[126:127]
	v_pk_mul_f32 v[14:15], v[134:135], v[14:15]
	v_pk_mul_f32 v[10:11], v[144:145], v[10:11]
	v_pk_mul_f32 v[6:7], v[130:131], v[6:7]
	v_pk_mul_f32 v[16:17], v[136:137], v[16:17]
	v_pk_mul_f32 v[12:13], v[146:147], v[12:13]
	v_pk_mul_f32 v[8:9], v[132:133], v[8:9]
	v_pk_mul_f32 v[4:5], v[128:129], v[4:5]
	v_pk_mul_f32 v[2:3], v[126:127], v[2:3]
	v_pk_mul_f32 v[56:57], v[132:133], v[56:57]
	v_pk_mul_f32 v[34:35], v[126:127], v[34:35]
	v_pk_mul_f32 v[36:37], v[36:37], v[128:129]
	v_pk_mul_f32 v[38:39], v[38:39], v[130:131]
	v_pk_mul_f32 v[40:41], v[40:41], v[132:133]
	v_pk_mul_f32 v[58:59], v[58:59], v[144:145]
	v_pk_mul_f32 v[42:43], v[42:43], v[144:145]
	v_pk_mul_f32 v[60:61], v[60:61], v[146:147]
	v_pk_mul_f32 v[44:45], v[44:45], v[146:147]
	v_pk_mul_f32 v[62:63], v[62:63], v[134:135]
	v_pk_mul_f32 v[46:47], v[46:47], v[134:135]
	v_pk_mul_f32 v[64:65], v[64:65], v[136:137]
	v_pk_mul_f32 v[48:49], v[48:49], v[136:137]

; __device__ __forceinline__ void finishSM(f32x16& p0, f32x16& p1, float alpha, float& l_reg, bf16x8& pa0, bf16x8& pa1, bf16x8& pa2, bf16x8& pa3) {
; #pragma unroll
;   for (int r = 0; r < 16; ++r) p1[r] = __builtin_amdgcn_exp2f(p1[r]);
;   float ps = 0;
; #pragma unroll
;   for (int r = 0; r < 16; ++r) ps += p0[r];
; #pragma unroll
;   for (int r = 0; r < 16; ++r) ps += p1[r];
;   { auto rr = __builtin_amdgcn_permlane32_swap(__float_as_uint(ps), __float_as_uint(ps), false, false);
;     ps = __uint_as_float(rr[0]) + __uint_as_float(rr[1]); }
;   l_reg = l_reg * alpha + ps;
;     ...
;   PK4(p0, 0, pa0); PK4(p0, 8, pa1); PK4(p1, 0, pa2); PK4(p1, 8, pa3);
; template <int DK, bool QL>
; __device__ __forceinline__ void qkt(f32x16& p0, f32x16& p1, const bf16* Ks, const bf16x8* qr, const char* ql, int r32, int hi) {
;   p0 = f32x16{}; p1 = f32x16{};
; #pragma unroll
;   for (int d0 = 0; d0 < DK / 16; ++d0) { int cb = (d0 * 16 + hi * 8) * 2;
;     const bf16x8 qv = QL ? *reinterpret_cast<const bf16x8*>(ql + d0 * 1024) : qr[d0];
;     bf16x8 b0 = *reinterpret_cast<const bf16x8*>((const char*)Ks + kswz<DK>(r32, cb));
;     bf16x8 b1 = *reinterpret_cast<const bf16x8*>((const char*)Ks + kswz<DK>(32 + r32, cb));
;     p0 = __builtin_amdgcn_mfma_f32_32x32x16_bf16(b0, qv, p0, 0, 0, 0);
;     p1 = __builtin_amdgcn_mfma_f32_32x32x16_bf16(b1, qv, p1, 0, 0, 0); }
.LBB0_701:
	ds_read_b128 v[66:69], v215 offset:49152
	ds_read_b128 v[70:73], v215 offset:53248
	v_exp_f32_e32 v143, v138
	v_add_f32_e32 v138, 0, v177
	v_add_f32_e32 v138, v226, v138
	s_waitcnt lgkmcnt(1)
	v_mfma_f32_32x32x16_bf16 v[82:97], v[66:69], v[110:113], 0
	v_add_f32_e32 v138, v161, v138
	v_add_f32_e32 v138, v223, v138
	v_add_f32_e32 v138, v153, v138
	ds_read_b128 v[228:231], v216 offset:49152
	ds_read_b128 v[232:235], v216 offset:53248
	v_add_f32_e32 v138, v176, v138
	v_add_f32_e32 v138, v152, v138
	v_add_f32_e32 v138, v160, v138
	s_waitcnt lgkmcnt(2)
	v_mfma_f32_32x32x16_bf16 v[66:81], v[70:73], v[110:113], 0
	v_add_f32_e32 v138, v149, v138
	v_add_f32_e32 v138, v151, v138
	v_add_f32_e32 v138, v147, v138
	v_add_f32_e32 v138, v150, v138
	v_add_f32_e32 v138, v145, v138
	v_exp_f32_e32 v164, v139
	v_add_f32_e32 v138, v148, v138
	s_waitcnt lgkmcnt(1)
	v_mfma_f32_32x32x16_bf16 v[82:97], v[228:231], v[106:109], v[82:97]
	v_exp_f32_e32 v136, v136
	v_add_f32_e32 v138, v144, v138
	v_exp_f32_e32 v137, v137
	v_add_f32_e32 v138, v146, v138
	v_exp_f32_e32 v130, v130
	v_add_f32_e32 v138, v143, v138
	v_exp_f32_e32 v131, v131
	s_waitcnt lgkmcnt(0)
	v_mfma_f32_32x32x16_bf16 v[66:81], v[232:235], v[106:109], v[66:81]
	ds_read_b128 v[228:231], v217 offset:49152
	ds_read_b128 v[232:235], v217 offset:53248
	v_add_f32_e32 v138, v164, v138
	v_exp_f32_e32 v128, v128
	v_add_f32_e32 v138, v136, v138
	v_exp_f32_e32 v129, v129
	v_add_f32_e32 v138, v137, v138
	v_exp_f32_e32 v126, v126
	s_waitcnt lgkmcnt(1)
	v_mfma_f32_32x32x16_bf16 v[82:97], v[228:231], v[102:105], v[82:97]
	v_add_f32_e32 v138, v130, v138
	v_exp_f32_e32 v127, v127
	v_add_f32_e32 v138, v131, v138
	v_exp_f32_e32 v165, v140
	v_add_f32_e32 v138, v128, v138
	v_exp_f32_e32 v166, v141
	v_add_f32_e32 v138, v129, v138
	s_waitcnt lgkmcnt(0)
	v_mfma_f32_32x32x16_bf16 v[66:81], v[232:235], v[102:105], v[66:81]
	ds_read_b128 v[228:231], v218 offset:49152
	ds_read_b128 v[232:235], v218 offset:53248
	v_exp_f32_e32 v134, v134
	v_add_f32_e32 v138, v126, v138
	v_exp_f32_e32 v135, v135
	v_add_f32_e32 v138, v127, v138
	v_exp_f32_e32 v132, v132
	v_add_f32_e32 v138, v165, v138
	s_waitcnt lgkmcnt(1)
	v_mfma_f32_32x32x16_bf16 v[82:97], v[228:231], v[98:101], v[82:97]
	v_exp_f32_e32 v133, v133
	v_add_f32_e32 v138, v166, v138
	v_add_f32_e32 v138, v134, v138
	v_add_f32_e32 v138, v135, v138
	v_add_f32_e32 v138, v132, v138
	v_add_f32_e32 v220, v133, v138
	v_mov_b32_e32 v221, v220
	s_waitcnt lgkmcnt(0)
	v_mfma_f32_32x32x16_bf16 v[66:81], v[232:235], v[98:101], v[66:81]
	v_cvt_pk_bf16_f32 v138, v177, v226
	v_cvt_pk_bf16_f32 v139, v161, v223
	v_cvt_pk_bf16_f32 v140, v153, v176
	v_cvt_pk_bf16_f32 v141, v152, v160
	v_cvt_pk_bf16_f32 v222, v149, v151
	v_cvt_pk_bf16_f32 v223, v147, v150
	v_cvt_pk_bf16_f32 v224, v145, v148
	v_permlane32_swap_b32_e32 v220, v221
	v_permlane32_swap_b32_e32 v138, v140
	v_cvt_pk_bf16_f32 v225, v144, v146
	v_permlane32_swap_b32_e32 v222, v224
	v_cvt_pk_bf16_f32 v144, v143, v164
	v_cvt_pk_bf16_f32 v145, v136, v137
	v_cvt_pk_bf16_f32 v146, v130, v131
	v_cvt_pk_bf16_f32 v147, v128, v129
	v_cvt_pk_bf16_f32 v148, v126, v127
	v_cvt_pk_bf16_f32 v149, v165, v166
	v_cvt_pk_bf16_f32 v150, v134, v135
	v_cvt_pk_bf16_f32 v151, v132, v133
	v_permlane32_swap_b32_e32 v139, v141
	v_permlane32_swap_b32_e32 v223, v225
	v_permlane32_swap_b32_e32 v144, v146
	v_permlane32_swap_b32_e32 v145, v147
	v_permlane32_swap_b32_e32 v148, v150
	v_permlane32_swap_b32_e32 v149, v151
	v_readlane_b32 s2, v254, 32
	v_readlane_b32 s3, v254, 33
	s_mov_b32 s4, 0xe0e0000
	s_mov_b32 s5, 0xe130000
	v_lshl_add_u64 v[160:161], v[156:157], 0, s[2:3]
	v_add_co_u32_e32 v126, vcc, s4, v160
	v_lshl_add_u64 v[176:177], v[158:159], 0, s[2:3]
	s_nop 0
	v_addc_co_u32_e32 v127, vcc, 0, v161, vcc
	v_add_co_u32_e32 v130, vcc, s5, v160
	s_nop 1
	v_addc_co_u32_e32 v131, vcc, 0, v161, vcc
	v_add_co_u32_e32 v134, vcc, s4, v176
	global_load_dwordx4 v[126:129], v[126:127], off offset:2048
	s_nop 0
	global_load_dwordx4 v[130:133], v[130:131], off offset:2048
	v_addc_co_u32_e32 v135, vcc, 0, v177, vcc
	global_load_dwordx4 v[134:137], v[134:135], off offset:1152
	ds_read_b64_tr_b16 v[226:227], v211 offset:0
	ds_read_b64_tr_b16 v[228:229], v211 offset:0x800
	ds_read_b64_tr_b16 v[230:231], v211 offset:0x1000
	ds_read_b64_tr_b16 v[232:233], v211 offset:0x1800
	ds_read_b64_tr_b16 v[234:235], v211 offset:0x2000
	ds_read_b64_tr_b16 v[236:237], v211 offset:0x2800
	ds_read_b64_tr_b16 v[238:239], v211 offset:0x3000
	ds_read_b64_tr_b16 v[240:241], v211 offset:0x3800
	s_waitcnt lgkmcnt(6)
	s_nop 0
	v_mfma_f32_32x32x16_bf16 v[2:17], v[138:141], v[226:229], v[2:17]
	ds_read_b64_tr_b16 v[226:227], v211 offset:0x200
	ds_read_b64_tr_b16 v[228:229], v211 offset:0xa00
	s_waitcnt lgkmcnt(6)
	v_mfma_f32_32x32x16_bf16 v[2:17], v[222:225], v[230:233], v[2:17]
	ds_read_b64_tr_b16 v[230:231], v211 offset:0x1200
	ds_read_b64_tr_b16 v[232:233], v211 offset:0x1a00
	s_waitcnt lgkmcnt(6)
	v_mfma_f32_32x32x16_bf16 v[2:17], v[144:147], v[234:237], v[2:17]
	ds_read_b64_tr_b16 v[234:235], v211 offset:0x2200
	ds_read_b64_tr_b16 v[236:237], v211 offset:0x2a00
	s_waitcnt lgkmcnt(6)
; #define SBAR() __builtin_amdgcn_sched_barrier(0)
; template <int D0> __device__ __forceinline__ void pv_one(f32x16& od, int vb, bf16x8 pa0, bf16x8 pa1, bf16x8 pa2, bf16x8 pa3) {
;   const s16x4 l0 = tr_read<v_rd_off(D0, 0, 0)>(vb), h0 = tr_read<v_rd_off(D0, 0, 1)>(vb), l1 = tr_read<v_rd_off(D0, 1, 0)>(vb), h1 = tr_read<v_rd_off(D0, 1, 1)>(vb);
;   const s16x4 l2 = tr_read<v_rd_off(D0, 2, 0)>(vb), h2 = tr_read<v_rd_off(D0, 2, 1)>(vb), l3 = tr_read<v_rd_off(D0, 3, 0)>(vb), h3 = tr_read<v_rd_off(D0, 3, 1)>(vb);
;   asm volatile("s_waitcnt lgkmcnt(0)" ::: "memory"); SBAR();
;     ...
;   od = __builtin_amdgcn_mfma_f32_32x32x16_bf16(pa0, PK(l0, h0), od, 0, 0, 0);
;   od = __builtin_amdgcn_mfma_f32_32x32x16_bf16(pa1, PK(l1, h1), od, 0, 0, 0);
;   od = __builtin_amdgcn_mfma_f32_32x32x16_bf16(pa2, PK(l2, h2), od, 0, 0, 0);
;   od = __builtin_amdgcn_mfma_f32_32x32x16_bf16(pa3, PK(l3, h3), od, 0, 0, 0);
;     ...
; }
; __device__ __forceinline__ void pv_d0(f32x16* o, int vb, bf16x8 pa0, bf16x8 pa1, bf16x8 pa2, bf16x8 pa3) {
;   pv_one<0>(o[0], vb, pa0, pa1, pa2, pa3); pv_one<1>(o[1], vb, pa0, pa1, pa2, pa3); pv_one<2>(o[2], vb, pa0, pa1, pa2, pa3); pv_one<3>(o[3], vb, pa0, pa1, pa2, pa3);
	v_mfma_f32_32x32x16_bf16 v[2:17], v[148:151], v[238:241], v[2:17]
	ds_read_b64_tr_b16 v[238:239], v211 offset:0x3200
	ds_read_b64_tr_b16 v[240:241], v211 offset:0x3a00
	s_waitcnt lgkmcnt(6)
	v_mfma_f32_32x32x16_bf16 v[50:65], v[138:141], v[226:229], v[50:65]
	ds_read_b64_tr_b16 v[226:227], v211 offset:0x400
	ds_read_b64_tr_b16 v[228:229], v211 offset:0xc00
	s_waitcnt lgkmcnt(6)
	v_mfma_f32_32x32x16_bf16 v[50:65], v[222:225], v[230:233], v[50:65]
	ds_read_b64_tr_b16 v[230:231], v211 offset:0x1400
	ds_read_b64_tr_b16 v[232:233], v211 offset:0x1c00
	s_waitcnt lgkmcnt(6)
	v_mfma_f32_32x32x16_bf16 v[50:65], v[144:147], v[234:237], v[50:65]
	ds_read_b64_tr_b16 v[234:235], v211 offset:0x2400
	ds_read_b64_tr_b16 v[236:237], v211 offset:0x2c00
	s_waitcnt lgkmcnt(6)
	v_mfma_f32_32x32x16_bf16 v[50:65], v[148:151], v[238:241], v[50:65]
	ds_read_b64_tr_b16 v[238:239], v211 offset:0x3400
	ds_read_b64_tr_b16 v[240:241], v211 offset:0x3c00
	s_waitcnt lgkmcnt(6)
	v_mfma_f32_32x32x16_bf16 v[34:49], v[138:141], v[226:229], v[34:49]
	ds_read_b64_tr_b16 v[226:227], v211 offset:0x600
	ds_read_b64_tr_b16 v[228:229], v211 offset:0xe00
	s_waitcnt lgkmcnt(6)
	v_mfma_f32_32x32x16_bf16 v[34:49], v[222:225], v[230:233], v[34:49]
	ds_read_b64_tr_b16 v[230:231], v211 offset:0x1600
	ds_read_b64_tr_b16 v[232:233], v211 offset:0x1e00
	s_waitcnt lgkmcnt(6)
	v_mfma_f32_32x32x16_bf16 v[34:49], v[144:147], v[234:237], v[34:49]
	ds_read_b64_tr_b16 v[234:235], v211 offset:0x2600
	ds_read_b64_tr_b16 v[236:237], v211 offset:0x2e00
	s_waitcnt lgkmcnt(6)
	v_mfma_f32_32x32x16_bf16 v[34:49], v[148:151], v[238:241], v[34:49]
	ds_read_b64_tr_b16 v[238:239], v211 offset:0x3600
	ds_read_b64_tr_b16 v[240:241], v211 offset:0x3e00
	s_waitcnt lgkmcnt(0)
	v_mfma_f32_32x32x16_bf16 v[18:33], v[138:141], v[226:229], v[18:33]
	v_max_f32_e32 v138, v83, v83
	v_max_f32_e32 v139, v82, v82
	v_max_f32_e32 v138, v139, v138
	v_max3_f32 v138, v138, v84, v85
	v_max3_f32 v138, v138, v86, v87
	v_max3_f32 v138, v138, v88, v89
	v_max3_f32 v138, v138, v90, v91
	v_max3_f32 v138, v138, v92, v93
	v_max3_f32 v138, v138, v94, v95
	v_mfma_f32_32x32x16_bf16 v[18:33], v[222:225], v[230:233], v[18:33]
	v_max3_f32 v138, v138, v96, v97
	v_max3_f32 v138, v138, v66, v67
	v_max3_f32 v138, v138, v68, v69
	v_max3_f32 v138, v138, v70, v71
	v_max3_f32 v138, v138, v72, v73
	v_max3_f32 v138, v138, v74, v75
	v_max3_f32 v138, v138, v76, v77
	v_max3_f32 v138, v138, v78, v79
	v_mfma_f32_32x32x16_bf16 v[18:33], v[144:147], v[234:237], v[18:33]
	v_max3_f32 v138, v138, v80, v81
	v_mov_b32_e32 v139, v138
	s_nop 1
	v_permlane32_swap_b32_e32 v138, v139
	v_max_f32_e32 v139, v139, v139
	v_max_f32_e32 v138, v138, v138
	v_max_f32_e32 v138, v138, v139
	v_sub_f32_e32 v139, v138, v142
	s_mov_b32 s2, 0x42800000
	v_cmp_ge_f32_e32 vcc, s2, v139
	v_max_f32_e32 v139, v142, v142
	v_max_f32_e32 v138, v139, v138
	v_mfma_f32_32x32x16_bf16 v[18:33], v[148:151], v[238:241], v[18:33]
	v_sub_f32_e32 v139, v142, v138
	v_mul_f32_e32 v139, 0x3e38aa3b, v139
	v_exp_f32_e32 v139, v139
	s_cmp_eq_u64 vcc, exec
	s_cselect_b64 s[2:3], -1, 0
	s_waitcnt vmcnt(3)
	v_cndmask_b32_e64 v222, v139, 1.0, s[2:3]
	v_cmp_gt_f32_e32 vcc, 1.0, v222
	s_waitcnt vmcnt(3)
	ds_write_b128 v214, v[122:125] offset:32768
	s_cbranch_vccz .LBB0_705
	s_and_saveexec_b64 s[4:5], s[0:1]
	ds_write_b32 v208, v222 offset:128
	s_or_b64 exec, exec, s[4:5]
	s_waitcnt lgkmcnt(0)
	v_add_u32_e32 v139, v207, v0
	ds_read_b128 v[144:147], v139 offset:224
	ds_read_b128 v[148:151], v139 offset:192
	ds_read_b128 v[224:227], v139 offset:160
	ds_read_b128 v[228:231], v139 offset:128
	s_waitcnt lgkmcnt(3)
	v_pk_mul_f32 v[14:15], v[14:15], v[144:145]
	s_waitcnt lgkmcnt(2)
	v_pk_mul_f32 v[10:11], v[10:11], v[148:149]
	s_waitcnt lgkmcnt(1)
	v_pk_mul_f32 v[6:7], v[6:7], v[224:225]
	v_pk_mul_f32 v[16:17], v[16:17], v[146:147]
	v_pk_mul_f32 v[12:13], v[12:13], v[150:151]
	v_pk_mul_f32 v[8:9], v[8:9], v[226:227]
	s_waitcnt lgkmcnt(0)
	v_pk_mul_f32 v[4:5], v[4:5], v[230:231]
	v_pk_mul_f32 v[2:3], v[2:3], v[228:229]
	v_pk_mul_f32 v[62:63], v[144:145], v[62:63]
	v_pk_mul_f32 v[58:59], v[148:149], v[58:59]
	v_pk_mul_f32 v[54:55], v[224:225], v[54:55]
	v_pk_mul_f32 v[64:65], v[146:147], v[64:65]
	v_pk_mul_f32 v[60:61], v[150:151], v[60:61]
	v_pk_mul_f32 v[56:57], v[226:227], v[56:57]
	v_pk_mul_f32 v[52:53], v[230:231], v[52:53]
	v_pk_mul_f32 v[50:51], v[228:229], v[50:51]
	v_pk_mul_f32 v[46:47], v[144:145], v[46:47]
	v_pk_mul_f32 v[42:43], v[148:149], v[42:43]
	v_pk_mul_f32 v[38:39], v[224:225], v[38:39]
	v_pk_mul_f32 v[48:49], v[146:147], v[48:49]
	v_pk_mul_f32 v[44:45], v[150:151], v[44:45]
	v_pk_mul_f32 v[40:41], v[226:227], v[40:41]
	v_pk_mul_f32 v[36:37], v[230:231], v[36:37]
	v_pk_mul_f32 v[34:35], v[228:229], v[34:35]
	v_pk_mul_f32 v[30:31], v[144:145], v[30:31]
	v_pk_mul_f32 v[26:27], v[148:149], v[26:27]
	v_pk_mul_f32 v[22:23], v[224:225], v[22:23]
	v_pk_mul_f32 v[32:33], v[146:147], v[32:33]
	v_pk_mul_f32 v[28:29], v[150:151], v[28:29]
	v_pk_mul_f32 v[24:25], v[226:227], v[24:25]
	v_pk_mul_f32 v[20:21], v[230:231], v[20:21]
	v_pk_mul_f32 v[18:19], v[228:229], v[18:19]

; #define SBAR() __builtin_amdgcn_sched_barrier(0)
; template <int D0> __device__ __forceinline__ void pv_one(f32x16& od, int vb, bf16x8 pa0, bf16x8 pa1, bf16x8 pa2, bf16x8 pa3) {
;   const s16x4 l0 = tr_read<v_rd_off(D0, 0, 0)>(vb), h0 = tr_read<v_rd_off(D0, 0, 1)>(vb), l1 = tr_read<v_rd_off(D0, 1, 0)>(vb), h1 = tr_read<v_rd_off(D0, 1, 1)>(vb);
;   const s16x4 l2 = tr_read<v_rd_off(D0, 2, 0)>(vb), h2 = tr_read<v_rd_off(D0, 2, 1)>(vb), l3 = tr_read<v_rd_off(D0, 3, 0)>(vb), h3 = tr_read<v_rd_off(D0, 3, 1)>(vb);
;   asm volatile("s_waitcnt lgkmcnt(0)" ::: "memory"); SBAR();
;     ...
;   od = __builtin_amdgcn_mfma_f32_32x32x16_bf16(pa0, PK(l0, h0), od, 0, 0, 0);
;   od = __builtin_amdgcn_mfma_f32_32x32x16_bf16(pa1, PK(l1, h1), od, 0, 0, 0);
;   od = __builtin_amdgcn_mfma_f32_32x32x16_bf16(pa2, PK(l2, h2), od, 0, 0, 0);
;   od = __builtin_amdgcn_mfma_f32_32x32x16_bf16(pa3, PK(l3, h3), od, 0, 0, 0);
;     ...
; }
; __device__ __forceinline__ void pv_d0(f32x16* o, int vb, bf16x8 pa0, bf16x8 pa1, bf16x8 pa2, bf16x8 pa3) {
;   pv_one<0>(o[0], vb, pa0, pa1, pa2, pa3); pv_one<1>(o[1], vb, pa0, pa1, pa2, pa3); pv_one<2>(o[2], vb, pa0, pa1, pa2, pa3); pv_one<3>(o[3], vb, pa0, pa1, pa2, pa3);
.LBB0_707:
	ds_read_b64_tr_b16 v[226:227], v210 offset:0
	ds_read_b64_tr_b16 v[228:229], v210 offset:0x800
	ds_read_b64_tr_b16 v[230:231], v210 offset:0x1000
	ds_read_b64_tr_b16 v[232:233], v210 offset:0x1800
	ds_read_b64_tr_b16 v[234:235], v210 offset:0x2000
	ds_read_b64_tr_b16 v[236:237], v210 offset:0x2800
	ds_read_b64_tr_b16 v[238:239], v210 offset:0x3000
	ds_read_b64_tr_b16 v[240:241], v210 offset:0x3800
	s_waitcnt lgkmcnt(6)
	s_nop 0
	v_mfma_f32_32x32x16_bf16 v[2:17], v[138:141], v[226:229], v[2:17]
	ds_read_b64_tr_b16 v[226:227], v210 offset:0x200
	ds_read_b64_tr_b16 v[228:229], v210 offset:0xa00
	s_waitcnt lgkmcnt(6)
	v_mfma_f32_32x32x16_bf16 v[2:17], v[142:145], v[230:233], v[2:17]
	ds_read_b64_tr_b16 v[230:231], v210 offset:0x1200
	ds_read_b64_tr_b16 v[232:233], v210 offset:0x1a00
	s_waitcnt lgkmcnt(6)
	v_mfma_f32_32x32x16_bf16 v[2:17], v[146:149], v[234:237], v[2:17]
	ds_read_b64_tr_b16 v[234:235], v210 offset:0x2200
	ds_read_b64_tr_b16 v[236:237], v210 offset:0x2a00
	s_waitcnt lgkmcnt(6)
	v_mfma_f32_32x32x16_bf16 v[2:17], v[150:153], v[238:241], v[2:17]
	ds_read_b64_tr_b16 v[238:239], v210 offset:0x3200
	ds_read_b64_tr_b16 v[240:241], v210 offset:0x3a00
	s_waitcnt lgkmcnt(6)
	v_mfma_f32_32x32x16_bf16 v[50:65], v[138:141], v[226:229], v[50:65]
	ds_read_b64_tr_b16 v[226:227], v210 offset:0x400
	ds_read_b64_tr_b16 v[228:229], v210 offset:0xc00
	s_waitcnt lgkmcnt(6)
	v_mfma_f32_32x32x16_bf16 v[50:65], v[142:145], v[230:233], v[50:65]
	ds_read_b64_tr_b16 v[230:231], v210 offset:0x1400
	ds_read_b64_tr_b16 v[232:233], v210 offset:0x1c00
	s_waitcnt lgkmcnt(6)
	v_mfma_f32_32x32x16_bf16 v[50:65], v[146:149], v[234:237], v[50:65]
	ds_read_b64_tr_b16 v[234:235], v210 offset:0x2400
	ds_read_b64_tr_b16 v[236:237], v210 offset:0x2c00
	s_waitcnt lgkmcnt(6)
	v_mfma_f32_32x32x16_bf16 v[50:65], v[150:153], v[238:241], v[50:65]
	ds_read_b64_tr_b16 v[238:239], v210 offset:0x3400
	ds_read_b64_tr_b16 v[240:241], v210 offset:0x3c00
	s_waitcnt lgkmcnt(6)
	v_mfma_f32_32x32x16_bf16 v[34:49], v[138:141], v[226:229], v[34:49]
	ds_read_b64_tr_b16 v[226:227], v210 offset:0x600
	ds_read_b64_tr_b16 v[228:229], v210 offset:0xe00
	s_waitcnt lgkmcnt(6)
	v_mfma_f32_32x32x16_bf16 v[34:49], v[142:145], v[230:233], v[34:49]
	ds_read_b64_tr_b16 v[230:231], v210 offset:0x1600
	ds_read_b64_tr_b16 v[232:233], v210 offset:0x1e00
	s_waitcnt lgkmcnt(6)
	v_mfma_f32_32x32x16_bf16 v[34:49], v[146:149], v[234:237], v[34:49]
	ds_read_b64_tr_b16 v[234:235], v210 offset:0x2600
	ds_read_b64_tr_b16 v[236:237], v210 offset:0x2e00
	s_waitcnt lgkmcnt(6)
	v_mfma_f32_32x32x16_bf16 v[34:49], v[150:153], v[238:241], v[34:49]
	ds_read_b64_tr_b16 v[238:239], v210 offset:0x3600
	ds_read_b64_tr_b16 v[240:241], v210 offset:0x3e00
	s_waitcnt lgkmcnt(0)
	v_mfma_f32_32x32x16_bf16 v[18:33], v[138:141], v[226:229], v[18:33]
	v_max_f32_e32 v138, v83, v83
	v_max_f32_e32 v139, v82, v82
	v_max_f32_e32 v138, v139, v138
	v_max3_f32 v138, v138, v84, v85
	v_max3_f32 v138, v138, v86, v87
	v_max3_f32 v138, v138, v88, v89
	v_max3_f32 v138, v138, v90, v91
	v_max3_f32 v138, v138, v92, v93
	v_max3_f32 v138, v138, v94, v95
	v_mfma_f32_32x32x16_bf16 v[18:33], v[142:145], v[230:233], v[18:33]
	v_max3_f32 v138, v138, v96, v97
	v_max3_f32 v138, v138, v66, v67
	v_max3_f32 v138, v138, v68, v69
	v_max3_f32 v138, v138, v70, v71
	v_max3_f32 v138, v138, v72, v73
	v_max3_f32 v138, v138, v74, v75
	v_max3_f32 v138, v138, v76, v77
	v_max3_f32 v138, v138, v78, v79
	v_mfma_f32_32x32x16_bf16 v[18:33], v[146:149], v[234:237], v[18:33]
	v_max3_f32 v138, v138, v80, v81
	v_mov_b32_e32 v139, v138
	s_nop 1
	v_permlane32_swap_b32_e32 v138, v139
	v_max_f32_e32 v139, v139, v139
	v_max_f32_e32 v138, v138, v138
	v_max_f32_e32 v138, v138, v139
	v_sub_f32_e32 v139, v138, v223
	s_mov_b32 s2, 0x42800000
	v_cmp_ge_f32_e32 vcc, s2, v139
	v_max_f32_e32 v139, v223, v223
	v_max_f32_e32 v138, v139, v138
	v_mfma_f32_32x32x16_bf16 v[18:33], v[150:153], v[238:241], v[18:33]
	v_sub_f32_e32 v139, v223, v138
	v_mul_f32_e32 v139, 0x3e38aa3b, v139
	v_exp_f32_e32 v139, v139
	s_cmp_eq_u64 vcc, exec
	s_cselect_b64 s[2:3], -1, 0
	s_waitcnt vmcnt(3)
	v_cndmask_b32_e64 v143, v139, 1.0, s[2:3]
	v_cmp_gt_f32_e32 vcc, 1.0, v143
	v_mov_b64_e32 v[182:183], v[126:127]
	v_mov_b64_e32 v[184:185], v[128:129]
	v_mov_b64_e32 v[194:195], v[130:131]
	v_mov_b64_e32 v[196:197], v[132:133]
	ds_write_b128 v214, v[134:137] offset:49152
	s_cbranch_vccz .LBB0_711
	s_and_saveexec_b64 s[6:7], s[0:1]
	ds_write_b32 v208, v143 offset:128
	s_or_b64 exec, exec, s[6:7]
	s_waitcnt lgkmcnt(0)
	v_add_u32_e32 v139, v207, v0
	ds_read_b128 v[126:129], v139 offset:224
	ds_read_b128 v[130:133], v139 offset:192
	ds_read_b128 v[134:137], v139 offset:160
	ds_read_b128 v[144:147], v139 offset:128
	s_waitcnt lgkmcnt(3)
	v_pk_mul_f32 v[14:15], v[14:15], v[126:127]
	s_waitcnt lgkmcnt(2)
	v_pk_mul_f32 v[10:11], v[10:11], v[130:131]
	s_waitcnt lgkmcnt(1)
	v_pk_mul_f32 v[6:7], v[6:7], v[134:135]
	v_pk_mul_f32 v[16:17], v[16:17], v[128:129]
	v_pk_mul_f32 v[12:13], v[12:13], v[132:133]
	v_pk_mul_f32 v[8:9], v[8:9], v[136:137]
	s_waitcnt lgkmcnt(0)
	v_pk_mul_f32 v[4:5], v[4:5], v[146:147]
	v_pk_mul_f32 v[2:3], v[2:3], v[144:145]
	v_pk_mul_f32 v[62:63], v[126:127], v[62:63]
	v_pk_mul_f32 v[58:59], v[130:131], v[58:59]
	v_pk_mul_f32 v[54:55], v[134:135], v[54:55]
	v_pk_mul_f32 v[64:65], v[128:129], v[64:65]
	v_pk_mul_f32 v[60:61], v[132:133], v[60:61]
	v_pk_mul_f32 v[56:57], v[136:137], v[56:57]
	v_pk_mul_f32 v[52:53], v[146:147], v[52:53]
	v_pk_mul_f32 v[50:51], v[144:145], v[50:51]
	v_pk_mul_f32 v[46:47], v[126:127], v[46:47]
	v_pk_mul_f32 v[42:43], v[130:131], v[42:43]
	v_pk_mul_f32 v[38:39], v[134:135], v[38:39]
	v_pk_mul_f32 v[48:49], v[128:129], v[48:49]
	v_pk_mul_f32 v[44:45], v[132:133], v[44:45]
	v_pk_mul_f32 v[40:41], v[136:137], v[40:41]
	v_pk_mul_f32 v[36:37], v[146:147], v[36:37]
	v_pk_mul_f32 v[34:35], v[144:145], v[34:35]
	v_pk_mul_f32 v[30:31], v[126:127], v[30:31]
	v_pk_mul_f32 v[26:27], v[130:131], v[26:27]
	v_pk_mul_f32 v[22:23], v[134:135], v[22:23]
	v_pk_mul_f32 v[32:33], v[128:129], v[32:33]
	v_pk_mul_f32 v[28:29], v[132:133], v[28:29]
	v_pk_mul_f32 v[24:25], v[136:137], v[24:25]
	v_pk_mul_f32 v[20:21], v[146:147], v[20:21]
	v_pk_mul_f32 v[18:19], v[144:145], v[18:19]
